# wave-uniform branch around the SK/SV address remap for tiles that do not hold sk/sv (hg, sq)
# speedup vs baseline: 1.0053x; 1.0016x over previous
; __device__ __forceinline__ unsigned cvt_pk_bf16(float lo, float hi) { unsigned r; asm volatile("v_cvt_pk_bf16_f32 %0, %1, %2" : "=v"(r) : "v"(lo), "v"(hi)); return r; }
; __device__ __forceinline__ float fsilu(float x) { return x * __builtin_amdgcn_rcpf(1.0f + __builtin_amdgcn_exp2f(-1.4426950408889634f * x)); }
;     __device__ __forceinline__ void operator()(const f32x4 (&acc)[2][2][4][2], const Unit& u, int wr, int wc, int fr, int fq) const {
;     ...
;         const int colg = tq * BM + wc * 32 + 8 * fq;
; #pragma unroll
;         for (int ai = 0; ai < 2; ++ai)
; #pragma unroll
;             for (int m = 0; m < 4; ++m) { const int row = row0 + ai * HALF + m * 16; const float rs = rsv[ai][m];
; #pragma unroll
;                 for (int bj = 0; bj < 2; ++bj) { f32x4 a = acc[ai][bj][m][0] * rs, b = acc[ai][bj][m][1] * rs; const size_t off = (size_t)row * 512 + colg + bj * HALF;
;                     if (grp == 1) { float* ZF = (float*)(ws + WS_ZF); *(f32x4*)(ZF + off) = a; *(f32x4*)(ZF + off + 4) = b; }
;                     else { if (grp == 0 || grp == 3) { a = (f32x4){fsilu(a[0]), fsilu(a[1]), fsilu(a[2]), fsilu(a[3])}; b = (f32x4){fsilu(b[0]), fsilu(b[1]), fsilu(b[2]), fsilu(b[3])}; }
;                         const size_t doff = grp == 0 ? WS_QH : (grp == 2 ? WS_VH : (grp == 3 ? WS_GH : WS_SV)); bf16_t* dst = (bf16_t*)(ws + doff);
;                         u32x4 w; w.x = cvt_pk_bf16(a[0], a[1]); w.y = cvt_pk_bf16(a[2], a[3]); w.z = cvt_pk_bf16(b[0], b[1]); w.w = cvt_pk_bf16(b[2], b[3]);
;                         *(u32x4*)(dst + off) = w; } } }
.LBB0_771:
	s_cmp_lg_u32 s1, 1
	s_cselect_b64 s[4:5], -1, 0
	s_cmp_eq_u32 s1, 3
	s_cselect_b64 s[10:11], -1, 0
	s_and_b64 s[30:31], s[10:11], exec
	s_mov_b32 s9, 0x7480000
	s_cselect_b32 s9, s9, 0xce80000
	s_cmp_lg_u32 s1, 2
	s_cselect_b32 s21, s9, 0x6440000
	s_cmp_lt_u32 s8, 2
	s_cselect_b64 s[8:9], -1, 0
	s_and_b64 s[30:31], s[8:9], exec
	s_cselect_b32 s21, 0x5400000, s21
	s_cmp_eq_u32 s21, 0xce80000
	s_cselect_b64 s[100:101], -1, 0
	v_readlane_b32 s98, v237, 2
	v_readlane_b32 s99, v237, 3
	s_nop 0
	s_add_u32 s98, s98, 0xce80000
	s_addc_u32 s99, s99, 0
	s_or_b64 s[8:9], s[8:9], s[10:11]
	v_lshl_or_b32 v189, s0, 8, v182
	v_lshlrev_b64 v[172:173], 9, v[166:167]
	v_cndmask_b32_e64 v136, 0, 1, s[8:9]
	v_or_b32_e32 v172, v172, v189
	s_waitcnt lgkmcnt(0)
	v_pk_mul_f32 v[130:131], v[126:127], v[170:171] op_sel_hi:[1,0]
	v_pk_mul_f32 v[128:129], v[124:125], v[170:171] op_sel_hi:[1,0]
	v_pk_mul_f32 v[134:135], v[122:123], v[170:171] op_sel_hi:[1,0]
	v_pk_mul_f32 v[132:133], v[120:121], v[170:171] op_sel_hi:[1,0]
	s_mov_b64 s[10:11], -1
	s_and_b64 vcc, exec, s[4:5]
	v_cmp_ne_u32_e64 s[8:9], 1, v136
	s_cbranch_vccz .LBB0_775
	v_mov_b64_e32 v[138:139], v[130:131]
	v_mov_b64_e32 v[142:143], v[134:135]
	s_and_b64 vcc, exec, s[8:9]
	v_mov_b64_e32 v[136:137], v[128:129]
	v_mov_b64_e32 v[140:141], v[132:133]
	s_cbranch_vccnz .LBB0_774
	v_mul_f32_e32 v136, 0xbfb8aa3b, v128
	v_mul_f32_e32 v137, 0xbfb8aa3b, v129
	v_mul_f32_e32 v138, 0xbfb8aa3b, v130
	v_mul_f32_e32 v139, 0xbfb8aa3b, v131
	v_mul_f32_e32 v140, 0xbfb8aa3b, v132
	v_mul_f32_e32 v141, 0xbfb8aa3b, v133
	v_mul_f32_e32 v142, 0xbfb8aa3b, v134
	v_mul_f32_e32 v143, 0xbfb8aa3b, v135
	v_exp_f32_e32 v136, v136
	v_exp_f32_e32 v137, v137
	v_exp_f32_e32 v138, v138
	v_exp_f32_e32 v139, v139
	v_exp_f32_e32 v140, v140
	v_exp_f32_e32 v141, v141
	v_exp_f32_e32 v142, v142
	v_exp_f32_e32 v143, v143
	v_add_f32_e32 v136, 1.0, v136
	v_add_f32_e32 v137, 1.0, v137
	v_add_f32_e32 v138, 1.0, v138
	v_add_f32_e32 v139, 1.0, v139
	v_add_f32_e32 v140, 1.0, v140
	v_add_f32_e32 v141, 1.0, v141
	v_add_f32_e32 v142, 1.0, v142
	v_add_f32_e32 v143, 1.0, v143
	v_rcp_f32_e32 v136, v136
	v_rcp_f32_e32 v137, v137
	v_rcp_f32_e32 v138, v138
	v_rcp_f32_e32 v139, v139
	v_rcp_f32_e32 v140, v140
	v_rcp_f32_e32 v142, v142
	v_rcp_f32_e32 v143, v143
	v_rcp_f32_e32 v141, v141
	v_pk_mul_f32 v[138:139], v[130:131], v[138:139]
	v_pk_mul_f32 v[136:137], v[128:129], v[136:137]
	v_pk_mul_f32 v[142:143], v[134:135], v[142:143]
	v_pk_mul_f32 v[140:141], v[132:133], v[140:141]
.LBB0_774:
	v_readlane_b32 s10, v237, 2
	v_readlane_b32 s11, v237, 3
	s_add_u32 s10, s10, s21
	s_addc_u32 s11, s11, 0
	v_cvt_pk_bf16_f32 v136, v136, v137
	v_cvt_pk_bf16_f32 v137, v138, v139
	v_cvt_pk_bf16_f32 v138, v140, v141
	v_lshl_add_u64 v[140:141], v[172:173], 1, s[10:11]
	s_mov_b64 s[10:11], 0
	v_cvt_pk_bf16_f32 v139, v142, v143
	s_mov_b64 vcc, s[100:101]
	s_cbranch_vccz .Lrm_orig_0
	v_accvgpr_write_b32 a0, v224
	v_accvgpr_write_b32 a1, v225
	v_accvgpr_write_b32 a2, v226
	v_accvgpr_write_b32 a3, v228
	v_accvgpr_write_b32 a4, v229
	v_subrev_u32_e32 v224, s98, v140
	v_lshrrev_b32_e32 v225, 10, v224
	v_and_b32_e32 v226, 0x3ff, v224
	v_lshrrev_b32_e32 v228, 7, v226
	v_mul_u32_u24_e32 v228, 0x204000, v228
	v_bfe_u32 v229, v226, 4, 2
	v_lshl_add_u32 v228, v229, 10, v228
	v_bfe_u32 v229, v226, 6, 1
	v_lshl_add_u32 v228, v229, 4, v228
	v_add_u32_e32 v229, 0x80, v225
	v_and_b32_e32 v226, 0xff, v225
	v_cmp_gt_u32_e32 vcc, 16, v226
	v_and_b32_e32 v224, 63, v226
	v_add_u32_e32 v226, 0x70, v226
	s_nop 1
	v_cndmask_b32_e32 v224, v224, v226, vcc
	v_cmp_lt_u32_e32 vcc, 0x3fff, v225
	s_nop 2
	v_cndmask_b32_e32 v229, v229, v224, vcc
	v_lshrrev_b32_e32 v224, 5, v229
	v_lshl_add_u32 v228, v224, 12, v228
	v_and_b32_e32 v224, 31, v229
	v_lshl_add_u32 v228, v224, 5, v228
	v_mov_b32_e32 v229, 0
	v_lshl_add_u64 v[224:225], s[98:99], 0, v[228:229]
	v_cmp_ne_u32_e64 vcc, s100, 0
	s_nop 2
	v_cndmask_b32_e32 v224, v140, v224, vcc
	v_cndmask_b32_e32 v225, v141, v225, vcc
	global_store_dwordx4 v[224:225], v[136:139], off
	s_nop 1
	v_accvgpr_read_b32 v224, a0
	v_accvgpr_read_b32 v225, a1
	v_accvgpr_read_b32 v226, a2
	v_accvgpr_read_b32 v228, a3
	v_accvgpr_read_b32 v229, a4
	s_branch .Lrm_done_0
.Lrm_orig_0:
	global_store_dwordx4 v[140:141], v[136:139], off
.Lrm_done_0:
.LBB0_775:
	s_and_b64 vcc, exec, s[10:11]
	s_cbranch_vccz .LBB0_777
	v_lshl_add_u64 v[136:137], v[172:173], 2, s[72:73]
	global_store_dwordx4 v[136:137], v[128:131], off
	global_store_dwordx4 v[136:137], v[132:135], off offset:16

; __device__ __forceinline__ unsigned cvt_pk_bf16(float lo, float hi) { unsigned r; asm volatile("v_cvt_pk_bf16_f32 %0, %1, %2" : "=v"(r) : "v"(lo), "v"(hi)); return r; }
; __device__ __forceinline__ float fsilu(float x) { return x * __builtin_amdgcn_rcpf(1.0f + __builtin_amdgcn_exp2f(-1.4426950408889634f * x)); }
;     __device__ __forceinline__ void operator()(const f32x4 (&acc)[2][2][4][2], const Unit& u, int wr, int wc, int fr, int fq) const {
;     ...
;             for (int m = 0; m < 4; ++m) { const int row = row0 + ai * HALF + m * 16; const float rs = rsv[ai][m];
; #pragma unroll
;                 for (int bj = 0; bj < 2; ++bj) { f32x4 a = acc[ai][bj][m][0] * rs, b = acc[ai][bj][m][1] * rs; const size_t off = (size_t)row * 512 + colg + bj * HALF;
;                     if (grp == 1) { float* ZF = (float*)(ws + WS_ZF); *(f32x4*)(ZF + off) = a; *(f32x4*)(ZF + off + 4) = b; }
;                     else { if (grp == 0 || grp == 3) { a = (f32x4){fsilu(a[0]), fsilu(a[1]), fsilu(a[2]), fsilu(a[3])}; b = (f32x4){fsilu(b[0]), fsilu(b[1]), fsilu(b[2]), fsilu(b[3])}; }
;                         const size_t doff = grp == 0 ? WS_QH : (grp == 2 ? WS_VH : (grp == 3 ? WS_GH : WS_SV)); bf16_t* dst = (bf16_t*)(ws + doff);
;                         u32x4 w; w.x = cvt_pk_bf16(a[0], a[1]); w.y = cvt_pk_bf16(a[2], a[3]); w.z = cvt_pk_bf16(b[0], b[1]); w.w = cvt_pk_bf16(b[2], b[3]);
;                         *(u32x4*)(dst + off) = w; } } }
.LBB0_780:
	v_readlane_b32 s4, v237, 2
	v_readlane_b32 s5, v237, 3
	s_add_u32 s4, s4, s21
	s_addc_u32 s5, s5, 0
	v_cvt_pk_bf16_f32 v136, v136, v137
	v_cvt_pk_bf16_f32 v137, v138, v139
	v_cvt_pk_bf16_f32 v138, v140, v141
	v_lshl_add_u64 v[140:141], v[172:173], 1, s[4:5]
	s_mov_b64 s[4:5], 0
	v_cvt_pk_bf16_f32 v139, v142, v143
	s_mov_b64 vcc, s[100:101]
	s_cbranch_vccz .Lrm_orig_1
	v_accvgpr_write_b32 a0, v224
	v_accvgpr_write_b32 a1, v225
	v_accvgpr_write_b32 a2, v226
	v_accvgpr_write_b32 a3, v228
	v_accvgpr_write_b32 a4, v229
	v_subrev_u32_e32 v224, s98, v140
	v_add_u32_e32 v224, 0x100, v224
	v_lshrrev_b32_e32 v225, 10, v224
	v_and_b32_e32 v226, 0x3ff, v224
	v_lshrrev_b32_e32 v228, 7, v226
	v_mul_u32_u24_e32 v228, 0x204000, v228
	v_bfe_u32 v229, v226, 4, 2
	v_lshl_add_u32 v228, v229, 10, v228
	v_bfe_u32 v229, v226, 6, 1
	v_lshl_add_u32 v228, v229, 4, v228
	v_add_u32_e32 v229, 0x80, v225
	v_and_b32_e32 v226, 0xff, v225
	v_cmp_gt_u32_e32 vcc, 16, v226
	v_and_b32_e32 v224, 63, v226
	v_add_u32_e32 v226, 0x70, v226
	s_nop 1
	v_cndmask_b32_e32 v224, v224, v226, vcc
	v_cmp_lt_u32_e32 vcc, 0x3fff, v225
	s_nop 2
	v_cndmask_b32_e32 v229, v229, v224, vcc
	v_lshrrev_b32_e32 v224, 5, v229
	v_lshl_add_u32 v228, v224, 12, v228
	v_and_b32_e32 v224, 31, v229
	v_lshl_add_u32 v228, v224, 5, v228
	v_mov_b32_e32 v229, 0
	v_lshl_add_u64 v[224:225], s[98:99], 0, v[228:229]
	v_mov_b32_e32 v228, 0x100
	v_lshl_add_u64 v[228:229], v[140:141], 0, v[228:229]
	v_cmp_ne_u32_e64 vcc, s100, 0
	s_nop 2
	v_cndmask_b32_e32 v224, v228, v224, vcc
	v_cndmask_b32_e32 v225, v229, v225, vcc
	global_store_dwordx4 v[224:225], v[136:139], off
	s_nop 1
	v_accvgpr_read_b32 v224, a0
	v_accvgpr_read_b32 v225, a1
	v_accvgpr_read_b32 v226, a2
	v_accvgpr_read_b32 v228, a3
	v_accvgpr_read_b32 v229, a4
	s_branch .Lrm_done_1
.Lrm_orig_1:
	global_store_dwordx4 v[140:141], v[136:139], off offset:256
.Lrm_done_1:
.LBB0_781:
	s_and_b64 vcc, exec, s[4:5]
	s_cbranch_vccz .LBB0_783
	v_lshlrev_b64 v[136:137], 2, v[172:173]
	v_or_b32_e32 v136, 0x200, v136
	v_lshl_add_u64 v[136:137], s[72:73], 0, v[136:137]
	global_store_dwordx4 v[136:137], v[128:131], off
	global_store_dwordx4 v[136:137], v[132:135], off offset:16

; __device__ __forceinline__ unsigned cvt_pk_bf16(float lo, float hi) { unsigned r; asm volatile("v_cvt_pk_bf16_f32 %0, %1, %2" : "=v"(r) : "v"(lo), "v"(hi)); return r; }
; __device__ __forceinline__ float fsilu(float x) { return x * __builtin_amdgcn_rcpf(1.0f + __builtin_amdgcn_exp2f(-1.4426950408889634f * x)); }
;     __device__ __forceinline__ void operator()(const f32x4 (&acc)[2][2][4][2], const Unit& u, int wr, int wc, int fr, int fq) const {
;     ...
;             for (int m = 0; m < 4; ++m) { const int row = row0 + ai * HALF + m * 16; const float rs = rsv[ai][m];
; #pragma unroll
;                 for (int bj = 0; bj < 2; ++bj) { f32x4 a = acc[ai][bj][m][0] * rs, b = acc[ai][bj][m][1] * rs; const size_t off = (size_t)row * 512 + colg + bj * HALF;
;                     if (grp == 1) { float* ZF = (float*)(ws + WS_ZF); *(f32x4*)(ZF + off) = a; *(f32x4*)(ZF + off + 4) = b; }
;                     else { if (grp == 0 || grp == 3) { a = (f32x4){fsilu(a[0]), fsilu(a[1]), fsilu(a[2]), fsilu(a[3])}; b = (f32x4){fsilu(b[0]), fsilu(b[1]), fsilu(b[2]), fsilu(b[3])}; }
;                         const size_t doff = grp == 0 ? WS_QH : (grp == 2 ? WS_VH : (grp == 3 ? WS_GH : WS_SV)); bf16_t* dst = (bf16_t*)(ws + doff);
;                         u32x4 w; w.x = cvt_pk_bf16(a[0], a[1]); w.y = cvt_pk_bf16(a[2], a[3]); w.z = cvt_pk_bf16(b[0], b[1]); w.w = cvt_pk_bf16(b[2], b[3]);
;                         *(u32x4*)(dst + off) = w; } } }
.LBB0_786:
	v_readlane_b32 s4, v237, 2
	v_readlane_b32 s5, v237, 3
	s_add_u32 s4, s4, s21
	s_addc_u32 s5, s5, 0
	v_cvt_pk_bf16_f32 v136, v136, v137
	v_cvt_pk_bf16_f32 v137, v138, v139
	v_cvt_pk_bf16_f32 v138, v140, v141
	v_lshl_add_u64 v[140:141], v[172:173], 1, s[4:5]
	s_mov_b64 s[4:5], 0
	v_cvt_pk_bf16_f32 v139, v142, v143
	s_mov_b64 vcc, s[100:101]
	s_cbranch_vccz .Lrm_orig_2
	v_accvgpr_write_b32 a0, v224
	v_accvgpr_write_b32 a1, v225
	v_accvgpr_write_b32 a2, v226
	v_accvgpr_write_b32 a3, v228
	v_accvgpr_write_b32 a4, v229
	v_subrev_u32_e32 v224, s98, v140
	v_lshrrev_b32_e32 v225, 10, v224
	v_and_b32_e32 v226, 0x3ff, v224
	v_lshrrev_b32_e32 v228, 7, v226
	v_mul_u32_u24_e32 v228, 0x204000, v228
	v_bfe_u32 v229, v226, 4, 2
	v_lshl_add_u32 v228, v229, 10, v228
	v_bfe_u32 v229, v226, 6, 1
	v_lshl_add_u32 v228, v229, 4, v228
	v_add_u32_e32 v229, 0x80, v225
	v_and_b32_e32 v226, 0xff, v225
	v_cmp_gt_u32_e32 vcc, 16, v226
	v_and_b32_e32 v224, 63, v226
	v_add_u32_e32 v226, 0x70, v226
	s_nop 1
	v_cndmask_b32_e32 v224, v224, v226, vcc
	v_cmp_lt_u32_e32 vcc, 0x3fff, v225
	s_nop 2
	v_cndmask_b32_e32 v229, v229, v224, vcc
	v_lshrrev_b32_e32 v224, 5, v229
	v_lshl_add_u32 v228, v224, 12, v228
	v_and_b32_e32 v224, 31, v229
	v_lshl_add_u32 v228, v224, 5, v228
	v_mov_b32_e32 v229, 0
	v_lshl_add_u64 v[224:225], s[98:99], 0, v[228:229]
	v_cmp_ne_u32_e64 vcc, s100, 0
	s_nop 2
	v_cndmask_b32_e32 v224, v140, v224, vcc
	v_cndmask_b32_e32 v225, v141, v225, vcc
	global_store_dwordx4 v[224:225], v[136:139], off
	s_nop 1
	v_accvgpr_read_b32 v224, a0
	v_accvgpr_read_b32 v225, a1
	v_accvgpr_read_b32 v226, a2
	v_accvgpr_read_b32 v228, a3
	v_accvgpr_read_b32 v229, a4
	s_branch .Lrm_done_2

;     __device__ __forceinline__ void operator()(const f32x4 (&acc)[2][2][4][2], const Unit& u, int wr, int wc, int fr, int fq) const {
;     ...
;                     if (grp == 1) { float* ZF = (float*)(ws + WS_ZF); *(f32x4*)(ZF + off) = a; *(f32x4*)(ZF + off + 4) = b; }
.Lrm_done_2:
.LBB0_787:
	s_and_b64 vcc, exec, s[4:5]
	s_cbranch_vccz .LBB0_789
	v_lshl_add_u64 v[136:137], v[172:173], 2, s[72:73]
	global_store_dwordx4 v[136:137], v[128:131], off
	global_store_dwordx4 v[136:137], v[132:135], off offset:16

; #define PG8_LAS __attribute__((address_space(3)))
; __device__ __forceinline__ unsigned cvt_pk_bf16(float lo, float hi) { unsigned r; asm volatile("v_cvt_pk_bf16_f32 %0, %1, %2" : "=v"(r) : "v"(lo), "v"(hi)); return r; }
;     __device__ __forceinline__ void operator()(const f32x4 (&acc)[2][2][4][2], const Unit& u, int wr, int wc, int fr, int fq) const {
;     ...
;         if (grp == 4 || grp == 5) {
;             bf16_t* dst = (bf16_t*)(ws + (grp == 4 ? WS_SQ : WS_SK)); const PG8_LAS float* gn = GL + (grp == 4 ? 0 : 64);
;             const int head = 4 * tq + wc;
;             f32x4 gv[2][2];
; #pragma unroll
;             for (int bj = 0; bj < 2; ++bj)
; #pragma unroll
;                 for (int n = 0; n < 2; ++n) gv[bj][n] = *(const PG8_LAS f32x4*)(gn + 32 * bj + 8 * fq + 4 * n);
; #pragma unroll
;             for (int ai = 0; ai < 2; ++ai)
; #pragma unroll
;                 for (int m = 0; m < 4; ++m) { const int row = row0 + ai * HALF + m * 16; const float rs = rsv[ai][m]; float sq = 0.f; f32x4 t[2][2];
; #pragma unroll
;                     for (int bj = 0; bj < 2; ++bj)
; #pragma unroll
;                         for (int n = 0; n < 2; ++n) { t[bj][n] = acc[ai][bj][m][n] * rs; sq += (t[bj][n][0] * t[bj][n][0] + t[bj][n][1] * t[bj][n][1]) + (t[bj][n][2] * t[bj][n][2] + t[bj][n][3] * t[bj][n][3]); }
;                     sq += __shfl_xor(sq, 16); sq += __shfl_xor(sq, 32);
;                     const float rn = 1.0f / sqrtf(sq * (1.0f / 64.0f) + 1e-6f);
; #pragma unroll
;                     for (int bj = 0; bj < 2; ++bj) { const f32x4 a = t[bj][0] * rn * gv[bj][0], b = t[bj][1] * rn * gv[bj][1];
;                         u32x4 w; w.x = cvt_pk_bf16(a[0], a[1]); w.y = cvt_pk_bf16(a[2], a[3]); w.z = cvt_pk_bf16(b[0], b[1]); w.w = cvt_pk_bf16(b[2], b[3]);
;                         *(u32x4*)(dst + (size_t)row * 512 + head * 64 + 32 * bj + 8 * fq) = w; } }
.LBB0_868:
	v_and_b32_e32 v129, 64, v188
	v_xor_b32_e32 v128, 16, v188
	v_add_u32_e32 v131, 64, v129
	v_cmp_lt_i32_e32 vcc, v128, v131
	s_waitcnt lgkmcnt(0)
	v_pk_mul_f32 v[142:143], v[126:127], v[170:171] op_sel_hi:[1,0]
	v_pk_mul_f32 v[172:173], v[124:125], v[170:171] op_sel_hi:[1,0]
	v_cndmask_b32_e32 v128, v188, v128, vcc
	v_pk_mul_f32 v[124:125], v[142:143], v[142:143]
	v_pk_mul_f32 v[126:127], v[172:173], v[172:173]
	v_pk_mul_f32 v[190:191], v[122:123], v[170:171] op_sel_hi:[1,0]
	v_pk_mul_f32 v[192:193], v[120:121], v[170:171] op_sel_hi:[1,0]
	v_pk_mul_f32 v[138:139], v[116:117], v[170:171] op_sel_hi:[1,0]
	v_lshlrev_b32_e32 v140, 2, v128
	v_pk_mov_b32 v[128:129], v[126:127], v[124:125] op_sel:[1,0]
	v_mov_b32_e32 v127, v125
	v_pk_mul_f32 v[120:121], v[190:191], v[190:191]
	v_pk_mul_f32 v[122:123], v[192:193], v[192:193]
	v_mul_f32_e32 v116, v138, v138
	v_pk_add_f32 v[124:125], v[128:129], v[126:127]
	v_pk_mov_b32 v[126:127], v[122:123], v[120:121] op_sel:[1,0]
	v_mov_b32_e32 v123, v121
	v_pk_mul_f32 v[136:137], v[118:119], v[170:171] op_sel_hi:[1,0]
	v_pk_fma_f32 v[116:117], v[138:139], v[138:139], v[116:117] op_sel_hi:[1,1,0]
	v_pk_add_f32 v[120:121], v[126:127], v[122:123]
	v_mul_f32_e32 v116, v136, v136
	v_pk_add_f32 v[124:125], v[124:125], v[124:125] op_sel_hi:[0,1]
	v_pk_add_f32 v[120:121], v[120:121], v[120:121] op_sel_hi:[0,1]
	v_pk_fma_f32 v[118:119], v[136:137], v[136:137], v[116:117] op_sel_hi:[1,1,0]
	v_pk_mul_f32 v[132:133], v[114:115], v[170:171] op_sel_hi:[1,0]
	v_pk_mul_f32 v[134:135], v[112:113], v[170:171] op_sel_hi:[1,0]
	v_mul_f32_e32 v124, v132, v132
	v_mul_f32_e32 v116, v134, v134
	v_mul_f32_e32 v118, v135, v135
	v_mul_f32_e32 v120, v133, v133
	v_pk_add_f32 v[112:113], v[116:117], v[118:119]
	v_pk_add_f32 v[114:115], v[124:125], v[120:121]
	s_cmp_eq_u32 s1, 4
	v_pk_add_f32 v[112:113], v[112:113], v[114:115]
	v_xor_b32_e32 v114, 32, v188
	v_add_f32_e32 v112, v112, v113
	ds_bpermute_b32 v113, v140, v112
	v_cmp_lt_i32_e32 vcc, v114, v131
	s_cselect_b64 s[4:5], -1, 0
	s_and_b64 s[4:5], s[4:5], exec
	v_cndmask_b32_e32 v114, v188, v114, vcc
	v_lshlrev_b32_e32 v141, 2, v114
	s_waitcnt lgkmcnt(0)
	v_add_f32_e32 v128, v112, v113
	ds_bpermute_b32 v129, v141, v128
	s_cselect_b32 s4, 0, 0x100
	s_mov_b32 s1, 0xae00000
	v_add_u32_e32 v130, s4, v181
	s_cselect_b32 s1, s1, 0xbe40000
	s_cselect_b64 s[100:101], 0, -1
	s_waitcnt lgkmcnt(0)
	v_add_f32_e32 v128, v128, v129
	v_fmamk_f32 v128, v128, 0x3c800000, v186
	v_mul_f32_e32 v129, 0x4f800000, v128
	v_cmp_gt_f32_e32 vcc, s50, v128
	ds_read_b128 v[124:127], v130
	ds_read_b128 v[120:123], v130 offset:16
	ds_read_b128 v[116:119], v130 offset:128
	ds_read_b128 v[112:115], v130 offset:144
	v_cndmask_b32_e32 v128, v128, v129, vcc
	v_sqrt_f32_e32 v129, v128
	v_readlane_b32 s4, v237, 2
	v_readlane_b32 s5, v237, 3
	s_add_u32 s8, s4, s1
	v_add_u32_e32 v130, -1, v129
	v_fma_f32 v131, -v130, v129, v128
	s_addc_u32 s9, s5, 0
	s_mov_b32 s98, s8
	s_mov_b32 s99, s9
	v_cmp_ge_f32_e64 s[4:5], 0, v131
	v_add_u32_e32 v131, 1, v129
	s_lshl_b32 s0, s0, 9
	v_cndmask_b32_e64 v130, v129, v130, s[4:5]
	v_fma_f32 v129, -v131, v129, v128
	v_cmp_lt_f32_e64 s[4:5], 0, v129
	s_or_b32 s10, s0, s49
	v_pk_mul_f32 v[94:95], v[94:95], v[168:169] op_sel_hi:[1,0]
	v_cndmask_b32_e64 v129, v130, v131, s[4:5]
	v_mul_f32_e32 v130, 0x37800000, v129
	v_cndmask_b32_e32 v129, v129, v130, vcc
	v_cmp_class_f32_e32 vcc, v128, v187
	v_pk_mul_f32 v[92:93], v[92:93], v[168:169] op_sel_hi:[1,0]
	v_pk_mul_f32 v[84:85], v[84:85], v[168:169] op_sel_hi:[1,0]
	v_cndmask_b32_e32 v128, v129, v128, vcc
	v_div_scale_f32 v129, s[0:1], v128, v128, 1.0
	v_rcp_f32_e32 v170, v129
	s_add_u32 s0, s8, s10
	s_addc_u32 s1, s9, 0
	v_lshl_add_u64 v[130:131], s[0:1], 0, v[152:153]
	v_fma_f32 v189, -v129, v170, 1.0
	v_fmac_f32_e32 v170, v189, v170
	v_div_scale_f32 v189, vcc, 1.0, v128, 1.0
	v_mul_f32_e32 v194, v189, v170
	v_fma_f32 v195, -v129, v194, v189
	v_fmac_f32_e32 v194, v195, v170
	v_fma_f32 v129, -v129, v194, v189
	v_div_fmas_f32 v129, v129, v170, v194
	v_div_fixup_f32 v170, v129, v128, 1.0
	v_pk_mul_f32 v[142:143], v[142:143], v[170:171] op_sel_hi:[1,0]
	v_pk_mul_f32 v[172:173], v[172:173], v[170:171] op_sel_hi:[1,0]
	s_waitcnt lgkmcnt(0)
	v_pk_mul_f32 v[142:143], v[126:127], v[142:143]
	v_pk_mul_f32 v[190:191], v[190:191], v[170:171] op_sel_hi:[1,0]
	v_lshlrev_b64 v[128:129], 10, v[166:167]
	v_pk_mul_f32 v[172:173], v[124:125], v[172:173]
	v_pk_mul_f32 v[192:193], v[192:193], v[170:171] op_sel_hi:[1,0]
	v_pk_mul_f32 v[194:195], v[122:123], v[190:191]
	v_cvt_pk_bf16_f32 v190, v172, v173
	v_cvt_pk_bf16_f32 v191, v142, v143
	v_mov_b32_e32 v142, v171
	v_lshl_add_u64 v[128:129], v[130:131], 0, v[128:129]
	v_pk_mul_f32 v[192:193], v[120:121], v[192:193]
	v_pk_mul_f32 v[110:111], v[110:111], v[142:143] op_sel_hi:[1,0]
	v_pk_mul_f32 v[108:109], v[108:109], v[142:143] op_sel_hi:[1,0]
	v_cvt_pk_bf16_f32 v192, v192, v193
	v_cvt_pk_bf16_f32 v193, v194, v195
	s_mov_b64 vcc, s[100:101]
	s_cbranch_vccz .Lrm_orig_16
	v_accvgpr_write_b32 a0, v224
	v_accvgpr_write_b32 a1, v225
	v_accvgpr_write_b32 a2, v226
	v_accvgpr_write_b32 a3, v228
	v_accvgpr_write_b32 a4, v229
	v_subrev_u32_e32 v224, s98, v128
	v_lshrrev_b32_e32 v225, 10, v224
	v_and_b32_e32 v226, 0x3ff, v224
	v_lshrrev_b32_e32 v228, 7, v226
	v_mul_u32_u24_e32 v228, 0x204000, v228
	v_and_b32_e32 v226, 0x70, v226
	v_lshl_add_u32 v228, v226, 5, v228
	v_add_u32_e32 v229, 0x80, v225
	v_and_b32_e32 v226, 0xff, v225
	v_cmp_gt_u32_e32 vcc, 16, v226
	v_and_b32_e32 v224, 63, v226
	v_add_u32_e32 v226, 0x70, v226
	s_nop 1
	v_cndmask_b32_e32 v224, v224, v226, vcc
	v_cmp_lt_u32_e32 vcc, 0x3fff, v225
	s_nop 2
	v_cndmask_b32_e32 v229, v229, v224, vcc
	v_lshrrev_b32_e32 v224, 5, v229
	v_lshl_add_u32 v228, v224, 12, v228
	v_and_b32_e32 v224, 31, v229
	v_lshl_add_u32 v228, v224, 4, v228
	v_mov_b32_e32 v229, 0
	v_lshl_add_u64 v[224:225], s[98:99], 0, v[228:229]
	v_cmp_ne_u32_e64 vcc, s100, 0
	s_nop 2
	v_cndmask_b32_e32 v224, v128, v224, vcc
	v_cndmask_b32_e32 v225, v129, v225, vcc
	global_store_dwordx4 v[224:225], v[190:193], off
	s_nop 1
	v_accvgpr_read_b32 v224, a0
	v_accvgpr_read_b32 v225, a1
	v_accvgpr_read_b32 v226, a2
	v_accvgpr_read_b32 v228, a3
	v_accvgpr_read_b32 v229, a4
	s_branch .Lrm_done_16
; __device__ __forceinline__ unsigned cvt_pk_bf16(float lo, float hi) { unsigned r; asm volatile("v_cvt_pk_bf16_f32 %0, %1, %2" : "=v"(r) : "v"(lo), "v"(hi)); return r; }
;     __device__ __forceinline__ void operator()(const f32x4 (&acc)[2][2][4][2], const Unit& u, int wr, int wc, int fr, int fq) const {
;     ...
;                 for (int m = 0; m < 4; ++m) { const int row = row0 + ai * HALF + m * 16; const float rs = rsv[ai][m]; float sq = 0.f; f32x4 t[2][2];
; #pragma unroll
;                     for (int bj = 0; bj < 2; ++bj)
; #pragma unroll
;                         for (int n = 0; n < 2; ++n) { t[bj][n] = acc[ai][bj][m][n] * rs; sq += (t[bj][n][0] * t[bj][n][0] + t[bj][n][1] * t[bj][n][1]) + (t[bj][n][2] * t[bj][n][2] + t[bj][n][3] * t[bj][n][3]); }
;                     sq += __shfl_xor(sq, 16); sq += __shfl_xor(sq, 32);
;                     const float rn = 1.0f / sqrtf(sq * (1.0f / 64.0f) + 1e-6f);
; #pragma unroll
;                     for (int bj = 0; bj < 2; ++bj) { const f32x4 a = t[bj][0] * rn * gv[bj][0], b = t[bj][1] * rn * gv[bj][1];
;                         u32x4 w; w.x = cvt_pk_bf16(a[0], a[1]); w.y = cvt_pk_bf16(a[2], a[3]); w.z = cvt_pk_bf16(b[0], b[1]); w.w = cvt_pk_bf16(b[2], b[3]);
;                         *(u32x4*)(dst + (size_t)row * 512 + head * 64 + 32 * bj + 8 * fq) = w; } }
.Lrm_orig_16:
	global_store_dwordx4 v[128:129], v[190:193], off
.Lrm_done_16:
	v_pk_mul_f32 v[172:173], v[110:111], v[110:111]
	v_pk_mul_f32 v[100:101], v[100:101], v[142:143] op_sel_hi:[1,0]
	v_pk_mul_f32 v[190:191], v[108:109], v[108:109]
	v_pk_mul_f32 v[102:103], v[102:103], v[142:143] op_sel_hi:[1,0]
	v_pk_mov_b32 v[192:193], v[190:191], v[172:173] op_sel:[1,0]
	v_mov_b32_e32 v191, v173
	v_pk_add_f32 v[172:173], v[192:193], v[190:191]
	v_pk_mul_f32 v[190:191], v[106:107], v[142:143] op_sel_hi:[1,0]
	v_pk_mul_f32 v[192:193], v[104:105], v[142:143] op_sel_hi:[1,0]
	v_pk_mul_f32 v[104:105], v[190:191], v[190:191]
	v_pk_mul_f32 v[106:107], v[192:193], v[192:193]
	v_pk_add_f32 v[172:173], v[172:173], v[172:173] op_sel_hi:[0,1]
	v_pk_mov_b32 v[194:195], v[106:107], v[104:105] op_sel:[1,0]
	v_mov_b32_e32 v107, v105
	v_pk_add_f32 v[104:105], v[194:195], v[106:107]
	v_pk_mul_f32 v[98:99], v[98:99], v[142:143] op_sel_hi:[1,0]
	v_pk_add_f32 v[104:105], v[104:105], v[104:105] op_sel_hi:[0,1]
	v_mul_f32_e32 v104, v100, v100
	v_pk_fma_f32 v[106:107], v[100:101], v[100:101], v[104:105] op_sel_hi:[1,1,0]
	v_mul_f32_e32 v104, v102, v102
	v_pk_fma_f32 v[194:195], v[102:103], v[102:103], v[104:105] op_sel_hi:[1,1,0]
	v_pk_mul_f32 v[96:97], v[96:97], v[142:143] op_sel_hi:[1,0]
	v_mul_f32_e32 v172, v98, v98
	v_mul_f32_e32 v106, v96, v96
	v_mul_f32_e32 v194, v97, v97
	v_mul_f32_e32 v104, v99, v99
	v_pk_add_f32 v[106:107], v[106:107], v[194:195]
	v_pk_add_f32 v[104:105], v[172:173], v[104:105]
	v_pk_mul_f32 v[134:135], v[134:135], v[170:171] op_sel_hi:[1,0]
	v_pk_add_f32 v[104:105], v[106:107], v[104:105]
	v_pk_mul_f32 v[106:107], v[136:137], v[170:171] op_sel_hi:[1,0]
	v_add_f32_e32 v142, v104, v105
	ds_bpermute_b32 v143, v140, v142
	v_pk_mul_f32 v[104:105], v[138:139], v[170:171] op_sel_hi:[1,0]
	v_pk_mul_f32 v[106:107], v[118:119], v[106:107]
	v_pk_mul_f32 v[104:105], v[116:117], v[104:105]
	v_pk_mul_f32 v[134:135], v[112:113], v[134:135]
	s_waitcnt lgkmcnt(0)
	v_add_f32_e32 v136, v142, v143
	ds_bpermute_b32 v137, v141, v136
	v_cvt_pk_bf16_f32 v104, v104, v105
	v_cvt_pk_bf16_f32 v105, v106, v107
	v_cvt_pk_bf16_f32 v106, v134, v135
	v_pk_mul_f32 v[132:133], v[132:133], v[170:171] op_sel_hi:[1,0]
	s_waitcnt lgkmcnt(0)
	v_add_f32_e32 v136, v136, v137
	v_fmamk_f32 v136, v136, 0x3c800000, v186
	v_mul_f32_e32 v137, 0x4f800000, v136
	v_cmp_gt_f32_e32 vcc, s50, v136
	v_pk_mul_f32 v[132:133], v[114:115], v[132:133]
	v_pk_mul_f32 v[86:87], v[86:87], v[168:169] op_sel_hi:[1,0]
	v_cndmask_b32_e32 v136, v136, v137, vcc
	v_sqrt_f32_e32 v137, v136
	v_pk_mul_f32 v[82:83], v[82:83], v[168:169] op_sel_hi:[1,0]
	v_pk_mul_f32 v[80:81], v[80:81], v[168:169] op_sel_hi:[1,0]
	v_pk_mul_f32 v[62:63], v[62:63], v[164:165] op_sel_hi:[1,0]
	v_add_u32_e32 v107, -1, v137
	v_fma_f32 v134, -v107, v137, v136
	v_cmp_ge_f32_e64 s[4:5], 0, v134
	v_add_u32_e32 v134, 1, v137
	v_fma_f32 v135, -v134, v137, v136
	v_cndmask_b32_e64 v107, v137, v107, s[4:5]
	v_cmp_lt_f32_e64 s[4:5], 0, v135
	v_pk_mul_f32 v[60:61], v[60:61], v[164:165] op_sel_hi:[1,0]
	v_pk_mul_f32 v[52:53], v[52:53], v[164:165] op_sel_hi:[1,0]
	v_cndmask_b32_e64 v107, v107, v134, s[4:5]
	v_mul_f32_e32 v134, 0x37800000, v107
	v_cndmask_b32_e32 v107, v107, v134, vcc
	v_cmp_class_f32_e32 vcc, v136, v187
	v_pk_mul_f32 v[54:55], v[54:55], v[164:165] op_sel_hi:[1,0]
	v_pk_mul_f32 v[50:51], v[50:51], v[164:165] op_sel_hi:[1,0]
	v_cndmask_b32_e32 v134, v107, v136, vcc
	v_div_scale_f32 v135, s[0:1], v134, v134, 1.0
	v_rcp_f32_e32 v136, v135
	v_cvt_pk_bf16_f32 v107, v132, v133
	s_mov_b64 vcc, s[100:101]
	s_cbranch_vccz .Lrm_orig_17
	v_accvgpr_write_b32 a0, v224
	v_accvgpr_write_b32 a1, v225
	v_accvgpr_write_b32 a2, v226
	v_accvgpr_write_b32 a3, v228
	v_accvgpr_write_b32 a4, v229
	v_subrev_u32_e32 v224, s98, v128
	v_add_u32_e32 v224, 64, v224
	v_lshrrev_b32_e32 v225, 10, v224
	v_and_b32_e32 v226, 0x3ff, v224
	v_lshrrev_b32_e32 v228, 7, v226
	v_mul_u32_u24_e32 v228, 0x204000, v228
	v_and_b32_e32 v226, 0x70, v226
	v_lshl_add_u32 v228, v226, 5, v228
	v_add_u32_e32 v229, 0x80, v225
	v_and_b32_e32 v226, 0xff, v225
	v_cmp_gt_u32_e32 vcc, 16, v226
	v_and_b32_e32 v224, 63, v226
	v_add_u32_e32 v226, 0x70, v226
	s_nop 1
	v_cndmask_b32_e32 v224, v224, v226, vcc
	v_cmp_lt_u32_e32 vcc, 0x3fff, v225
	s_nop 2
	v_cndmask_b32_e32 v229, v229, v224, vcc
	v_lshrrev_b32_e32 v224, 5, v229
	v_lshl_add_u32 v228, v224, 12, v228
	v_and_b32_e32 v224, 31, v229
	v_lshl_add_u32 v228, v224, 4, v228
	v_mov_b32_e32 v229, 0
	v_lshl_add_u64 v[224:225], s[98:99], 0, v[228:229]
	v_lshl_add_u64 v[228:229], v[128:129], 0, 64
	v_cmp_ne_u32_e64 vcc, s100, 0
	s_nop 2
	v_cndmask_b32_e32 v224, v228, v224, vcc
	v_cndmask_b32_e32 v225, v229, v225, vcc
	global_store_dwordx4 v[224:225], v[104:107], off
	s_nop 1
	v_accvgpr_read_b32 v224, a0
	v_accvgpr_read_b32 v225, a1
	v_accvgpr_read_b32 v226, a2
	v_accvgpr_read_b32 v228, a3
	v_accvgpr_read_b32 v229, a4
	s_branch .Lrm_done_17
.Lrm_orig_17:
	global_store_dwordx4 v[128:129], v[104:107], off offset:64
; __device__ __forceinline__ unsigned cvt_pk_bf16(float lo, float hi) { unsigned r; asm volatile("v_cvt_pk_bf16_f32 %0, %1, %2" : "=v"(r) : "v"(lo), "v"(hi)); return r; }
;     __device__ __forceinline__ void operator()(const f32x4 (&acc)[2][2][4][2], const Unit& u, int wr, int wc, int fr, int fq) const {
;     ...
;                 for (int m = 0; m < 4; ++m) { const int row = row0 + ai * HALF + m * 16; const float rs = rsv[ai][m]; float sq = 0.f; f32x4 t[2][2];
; #pragma unroll
;                     for (int bj = 0; bj < 2; ++bj)
; #pragma unroll
;                         for (int n = 0; n < 2; ++n) { t[bj][n] = acc[ai][bj][m][n] * rs; sq += (t[bj][n][0] * t[bj][n][0] + t[bj][n][1] * t[bj][n][1]) + (t[bj][n][2] * t[bj][n][2] + t[bj][n][3] * t[bj][n][3]); }
;                     sq += __shfl_xor(sq, 16); sq += __shfl_xor(sq, 32);
;                     const float rn = 1.0f / sqrtf(sq * (1.0f / 64.0f) + 1e-6f);
; #pragma unroll
;                     for (int bj = 0; bj < 2; ++bj) { const f32x4 a = t[bj][0] * rn * gv[bj][0], b = t[bj][1] * rn * gv[bj][1];
;                         u32x4 w; w.x = cvt_pk_bf16(a[0], a[1]); w.y = cvt_pk_bf16(a[2], a[3]); w.z = cvt_pk_bf16(b[0], b[1]); w.w = cvt_pk_bf16(b[2], b[3]);
;                         *(u32x4*)(dst + (size_t)row * 512 + head * 64 + 32 * bj + 8 * fq) = w; } }
.Lrm_done_17:
	v_pk_mul_f32 v[48:49], v[48:49], v[164:165] op_sel_hi:[1,0]
	v_pk_mul_f32 v[30:31], v[30:31], v[162:163] op_sel_hi:[1,0]
	v_fma_f32 v105, -v135, v136, 1.0
	v_fmac_f32_e32 v136, v105, v136
	v_div_scale_f32 v105, vcc, 1.0, v134, 1.0
	v_mul_f32_e32 v106, v105, v136
	v_fma_f32 v107, -v135, v106, v105
	v_fmac_f32_e32 v106, v107, v136
	v_fma_f32 v105, -v135, v106, v105
	v_or_b32_e32 v104, 16, v166
	v_div_fmas_f32 v105, v105, v136, v106
	v_div_fixup_f32 v132, v105, v134, 1.0
	v_ashrrev_i32_e32 v105, 31, v104
	v_lshlrev_b64 v[104:105], 10, v[104:105]
	v_lshl_add_u64 v[134:135], v[130:131], 0, v[104:105]
	v_pk_mul_f32 v[104:105], v[108:109], v[132:133] op_sel_hi:[1,0]
	v_pk_mul_f32 v[106:107], v[110:111], v[132:133] op_sel_hi:[1,0]
	v_pk_mul_f32 v[104:105], v[124:125], v[104:105]
	v_pk_mul_f32 v[106:107], v[126:127], v[106:107]
	v_pk_mul_f32 v[108:109], v[192:193], v[132:133] op_sel_hi:[1,0]
	v_pk_mul_f32 v[110:111], v[190:191], v[132:133] op_sel_hi:[1,0]
	v_pk_mul_f32 v[108:109], v[120:121], v[108:109]
	v_pk_mul_f32 v[110:111], v[122:123], v[110:111]
	v_cvt_pk_bf16_f32 v104, v104, v105
	v_cvt_pk_bf16_f32 v105, v106, v107
	v_cvt_pk_bf16_f32 v106, v108, v109
	v_pk_mul_f32 v[96:97], v[96:97], v[132:133] op_sel_hi:[1,0]
	v_cvt_pk_bf16_f32 v107, v110, v111
	s_mov_b64 vcc, s[100:101]
	s_cbranch_vccz .Lrm_orig_18
	v_accvgpr_write_b32 a0, v224
	v_accvgpr_write_b32 a1, v225
	v_accvgpr_write_b32 a2, v226
	v_accvgpr_write_b32 a3, v228
	v_accvgpr_write_b32 a4, v229
	v_subrev_u32_e32 v224, s98, v134
	v_lshrrev_b32_e32 v225, 10, v224
	v_and_b32_e32 v226, 0x3ff, v224
	v_lshrrev_b32_e32 v228, 7, v226
	v_mul_u32_u24_e32 v228, 0x204000, v228
	v_and_b32_e32 v226, 0x70, v226
	v_lshl_add_u32 v228, v226, 5, v228
	v_add_u32_e32 v229, 0x80, v225
	v_and_b32_e32 v226, 0xff, v225
	v_cmp_gt_u32_e32 vcc, 16, v226
	v_and_b32_e32 v224, 63, v226
	v_add_u32_e32 v226, 0x70, v226
	s_nop 1
	v_cndmask_b32_e32 v224, v224, v226, vcc
	v_cmp_lt_u32_e32 vcc, 0x3fff, v225
	s_nop 2
	v_cndmask_b32_e32 v229, v229, v224, vcc
	v_lshrrev_b32_e32 v224, 5, v229
	v_lshl_add_u32 v228, v224, 12, v228
	v_and_b32_e32 v224, 31, v229
	v_lshl_add_u32 v228, v224, 4, v228
	v_mov_b32_e32 v229, 0
	v_lshl_add_u64 v[224:225], s[98:99], 0, v[228:229]
	v_cmp_ne_u32_e64 vcc, s100, 0
	s_nop 2
	v_cndmask_b32_e32 v224, v134, v224, vcc
	v_cndmask_b32_e32 v225, v135, v225, vcc
	global_store_dwordx4 v[224:225], v[104:107], off
	s_nop 1
	v_accvgpr_read_b32 v224, a0
	v_accvgpr_read_b32 v225, a1
	v_accvgpr_read_b32 v226, a2
	v_accvgpr_read_b32 v228, a3
	v_accvgpr_read_b32 v229, a4
	s_branch .Lrm_done_18
.Lrm_orig_18:
	global_store_dwordx4 v[134:135], v[104:107], off
.Lrm_done_18:
	v_pk_mul_f32 v[96:97], v[112:113], v[96:97]
	v_pk_mul_f32 v[98:99], v[98:99], v[132:133] op_sel_hi:[1,0]
	v_pk_mul_f32 v[104:105], v[94:95], v[94:95]
	v_pk_mul_f32 v[106:107], v[92:93], v[92:93]
	v_pk_mul_f32 v[98:99], v[114:115], v[98:99]
	v_pk_mov_b32 v[108:109], v[106:107], v[104:105] op_sel:[1,0]
	v_mov_b32_e32 v107, v105
	v_pk_add_f32 v[104:105], v[108:109], v[106:107]
	v_pk_mul_f32 v[106:107], v[90:91], v[168:169] op_sel_hi:[1,0]
	v_pk_mul_f32 v[108:109], v[88:89], v[168:169] op_sel_hi:[1,0]
	v_pk_mul_f32 v[88:89], v[106:107], v[106:107]
	v_pk_mul_f32 v[90:91], v[108:109], v[108:109]
	v_pk_add_f32 v[104:105], v[104:105], v[104:105] op_sel_hi:[0,1]
	v_pk_mov_b32 v[110:111], v[90:91], v[88:89] op_sel:[1,0]
	v_mov_b32_e32 v91, v89
	v_pk_add_f32 v[88:89], v[110:111], v[90:91]
	v_mul_f32_e32 v104, v82, v82
	v_pk_add_f32 v[88:89], v[88:89], v[88:89] op_sel_hi:[0,1]
	v_mul_f32_e32 v88, v84, v84
	v_pk_fma_f32 v[90:91], v[84:85], v[84:85], v[88:89] op_sel_hi:[1,1,0]
	v_mul_f32_e32 v88, v86, v86
	v_pk_fma_f32 v[110:111], v[86:87], v[86:87], v[88:89] op_sel_hi:[1,1,0]
	v_mul_f32_e32 v90, v80, v80
	v_mul_f32_e32 v110, v81, v81
	v_mul_f32_e32 v88, v83, v83
	v_pk_add_f32 v[90:91], v[90:91], v[110:111]
	v_pk_add_f32 v[88:89], v[104:105], v[88:89]
	v_pk_mul_f32 v[28:29], v[28:29], v[162:163] op_sel_hi:[1,0]
	v_pk_add_f32 v[88:89], v[90:91], v[88:89]
	v_pk_mul_f32 v[90:91], v[102:103], v[132:133] op_sel_hi:[1,0]
	v_add_f32_e32 v104, v88, v89
	ds_bpermute_b32 v105, v140, v104
	v_pk_mul_f32 v[88:89], v[100:101], v[132:133] op_sel_hi:[1,0]
	v_pk_mul_f32 v[90:91], v[118:119], v[90:91]
	v_pk_mul_f32 v[88:89], v[116:117], v[88:89]
	v_pk_mul_f32 v[20:21], v[20:21], v[162:163] op_sel_hi:[1,0]
	s_waitcnt lgkmcnt(0)
	v_add_f32_e32 v100, v104, v105
	ds_bpermute_b32 v101, v141, v100
	v_cvt_pk_bf16_f32 v88, v88, v89
	v_cvt_pk_bf16_f32 v89, v90, v91
	v_cvt_pk_bf16_f32 v90, v96, v97
	v_pk_mul_f32 v[22:23], v[22:23], v[162:163] op_sel_hi:[1,0]
	s_waitcnt lgkmcnt(0)
	v_add_f32_e32 v100, v100, v101
	v_fmamk_f32 v100, v100, 0x3c800000, v186
	v_mul_f32_e32 v101, 0x4f800000, v100
	v_cmp_gt_f32_e32 vcc, s50, v100
	v_pk_mul_f32 v[18:19], v[18:19], v[162:163] op_sel_hi:[1,0]
	v_pk_mul_f32 v[16:17], v[16:17], v[162:163] op_sel_hi:[1,0]
	v_cndmask_b32_e32 v100, v100, v101, vcc
	v_sqrt_f32_e32 v101, v100
	s_nop 0
	v_add_u32_e32 v91, -1, v101
	v_fma_f32 v96, -v91, v101, v100
	v_cmp_ge_f32_e64 s[4:5], 0, v96
	v_add_u32_e32 v96, 1, v101
	v_fma_f32 v97, -v96, v101, v100
	v_cndmask_b32_e64 v91, v101, v91, s[4:5]
	v_cmp_lt_f32_e64 s[4:5], 0, v97
	s_nop 1
	v_cndmask_b32_e64 v91, v91, v96, s[4:5]
	v_mul_f32_e32 v96, 0x37800000, v91
	v_cndmask_b32_e32 v91, v91, v96, vcc
	v_cmp_class_f32_e32 vcc, v100, v187
	s_nop 1
	v_cndmask_b32_e32 v96, v91, v100, vcc
	v_div_scale_f32 v97, s[0:1], v96, v96, 1.0
	v_rcp_f32_e32 v100, v97
	v_cvt_pk_bf16_f32 v91, v98, v99
	s_mov_b64 vcc, s[100:101]
	s_cbranch_vccz .Lrm_orig_19
	v_accvgpr_write_b32 a0, v224
	v_accvgpr_write_b32 a1, v225
	v_accvgpr_write_b32 a2, v226
	v_accvgpr_write_b32 a3, v228
	v_accvgpr_write_b32 a4, v229
	v_subrev_u32_e32 v224, s98, v134
	v_add_u32_e32 v224, 64, v224
	v_lshrrev_b32_e32 v225, 10, v224
	v_and_b32_e32 v226, 0x3ff, v224
	v_lshrrev_b32_e32 v228, 7, v226
	v_mul_u32_u24_e32 v228, 0x204000, v228
	v_and_b32_e32 v226, 0x70, v226
	v_lshl_add_u32 v228, v226, 5, v228
	v_add_u32_e32 v229, 0x80, v225
	v_and_b32_e32 v226, 0xff, v225
	v_cmp_gt_u32_e32 vcc, 16, v226
	v_and_b32_e32 v224, 63, v226
	v_add_u32_e32 v226, 0x70, v226
	s_nop 1
	v_cndmask_b32_e32 v224, v224, v226, vcc
	v_cmp_lt_u32_e32 vcc, 0x3fff, v225
	s_nop 2
	v_cndmask_b32_e32 v229, v229, v224, vcc
	v_lshrrev_b32_e32 v224, 5, v229
	v_lshl_add_u32 v228, v224, 12, v228
	v_and_b32_e32 v224, 31, v229
	v_lshl_add_u32 v228, v224, 4, v228
	v_mov_b32_e32 v229, 0
	v_lshl_add_u64 v[224:225], s[98:99], 0, v[228:229]
	v_lshl_add_u64 v[228:229], v[134:135], 0, 64
	v_cmp_ne_u32_e64 vcc, s100, 0
	s_nop 2
	v_cndmask_b32_e32 v224, v228, v224, vcc
	v_cndmask_b32_e32 v225, v229, v225, vcc
	global_store_dwordx4 v[224:225], v[88:91], off
	s_nop 1
	v_accvgpr_read_b32 v224, a0
	v_accvgpr_read_b32 v225, a1
	v_accvgpr_read_b32 v226, a2
	v_accvgpr_read_b32 v228, a3
	v_accvgpr_read_b32 v229, a4
	s_branch .Lrm_done_19
; __device__ __forceinline__ unsigned cvt_pk_bf16(float lo, float hi) { unsigned r; asm volatile("v_cvt_pk_bf16_f32 %0, %1, %2" : "=v"(r) : "v"(lo), "v"(hi)); return r; }
;     __device__ __forceinline__ void operator()(const f32x4 (&acc)[2][2][4][2], const Unit& u, int wr, int wc, int fr, int fq) const {
;     ...
;                 for (int m = 0; m < 4; ++m) { const int row = row0 + ai * HALF + m * 16; const float rs = rsv[ai][m]; float sq = 0.f; f32x4 t[2][2];
; #pragma unroll
;                     for (int bj = 0; bj < 2; ++bj)
; #pragma unroll
;                         for (int n = 0; n < 2; ++n) { t[bj][n] = acc[ai][bj][m][n] * rs; sq += (t[bj][n][0] * t[bj][n][0] + t[bj][n][1] * t[bj][n][1]) + (t[bj][n][2] * t[bj][n][2] + t[bj][n][3] * t[bj][n][3]); }
;                     sq += __shfl_xor(sq, 16); sq += __shfl_xor(sq, 32);
;                     const float rn = 1.0f / sqrtf(sq * (1.0f / 64.0f) + 1e-6f);
; #pragma unroll
;                     for (int bj = 0; bj < 2; ++bj) { const f32x4 a = t[bj][0] * rn * gv[bj][0], b = t[bj][1] * rn * gv[bj][1];
;                         u32x4 w; w.x = cvt_pk_bf16(a[0], a[1]); w.y = cvt_pk_bf16(a[2], a[3]); w.z = cvt_pk_bf16(b[0], b[1]); w.w = cvt_pk_bf16(b[2], b[3]);
;                         *(u32x4*)(dst + (size_t)row * 512 + head * 64 + 32 * bj + 8 * fq) = w; } }
.Lrm_orig_19:
	global_store_dwordx4 v[134:135], v[88:91], off offset:64
.Lrm_done_19:
	s_nop 1
	v_fma_f32 v89, -v97, v100, 1.0
	v_fmac_f32_e32 v100, v89, v100
	v_div_scale_f32 v89, vcc, 1.0, v96, 1.0
	v_mul_f32_e32 v90, v89, v100
	v_fma_f32 v91, -v97, v90, v89
	v_fmac_f32_e32 v90, v91, v100
	v_fma_f32 v89, -v97, v90, v89
	v_or_b32_e32 v88, 32, v166
	v_div_fmas_f32 v89, v89, v100, v90
	v_div_fixup_f32 v96, v89, v96, 1.0
	v_ashrrev_i32_e32 v89, 31, v88
	v_lshlrev_b64 v[88:89], 10, v[88:89]
	v_lshl_add_u64 v[98:99], v[130:131], 0, v[88:89]
	v_pk_mul_f32 v[88:89], v[92:93], v[96:97] op_sel_hi:[1,0]
	v_pk_mul_f32 v[90:91], v[94:95], v[96:97] op_sel_hi:[1,0]
	v_pk_mul_f32 v[88:89], v[124:125], v[88:89]
	v_pk_mul_f32 v[90:91], v[126:127], v[90:91]
	v_pk_mul_f32 v[92:93], v[108:109], v[96:97] op_sel_hi:[1,0]
	v_pk_mul_f32 v[94:95], v[106:107], v[96:97] op_sel_hi:[1,0]
	v_cvt_pk_bf16_f32 v88, v88, v89
	v_pk_mul_f32 v[92:93], v[120:121], v[92:93]
	v_pk_mul_f32 v[94:95], v[122:123], v[94:95]
	v_cvt_pk_bf16_f32 v89, v90, v91
	v_cvt_pk_bf16_f32 v90, v92, v93
	v_pk_mul_f32 v[80:81], v[80:81], v[96:97] op_sel_hi:[1,0]
	v_cvt_pk_bf16_f32 v91, v94, v95
	s_mov_b64 vcc, s[100:101]
	s_cbranch_vccz .Lrm_orig_20
	v_accvgpr_write_b32 a0, v224
	v_accvgpr_write_b32 a1, v225
	v_accvgpr_write_b32 a2, v226
	v_accvgpr_write_b32 a3, v228
	v_accvgpr_write_b32 a4, v229
	v_subrev_u32_e32 v224, s98, v98
	v_lshrrev_b32_e32 v225, 10, v224
	v_and_b32_e32 v226, 0x3ff, v224
	v_lshrrev_b32_e32 v228, 7, v226
	v_mul_u32_u24_e32 v228, 0x204000, v228
	v_and_b32_e32 v226, 0x70, v226
	v_lshl_add_u32 v228, v226, 5, v228
	v_add_u32_e32 v229, 0x80, v225
	v_and_b32_e32 v226, 0xff, v225
	v_cmp_gt_u32_e32 vcc, 16, v226
	v_and_b32_e32 v224, 63, v226
	v_add_u32_e32 v226, 0x70, v226
	s_nop 1
	v_cndmask_b32_e32 v224, v224, v226, vcc
	v_cmp_lt_u32_e32 vcc, 0x3fff, v225
	s_nop 2
	v_cndmask_b32_e32 v229, v229, v224, vcc
	v_lshrrev_b32_e32 v224, 5, v229
	v_lshl_add_u32 v228, v224, 12, v228
	v_and_b32_e32 v224, 31, v229
	v_lshl_add_u32 v228, v224, 4, v228
	v_mov_b32_e32 v229, 0
	v_lshl_add_u64 v[224:225], s[98:99], 0, v[228:229]
	v_cmp_ne_u32_e64 vcc, s100, 0
	s_nop 2
	v_cndmask_b32_e32 v224, v98, v224, vcc
	v_cndmask_b32_e32 v225, v99, v225, vcc
	global_store_dwordx4 v[224:225], v[88:91], off
	s_nop 1
	v_accvgpr_read_b32 v224, a0
	v_accvgpr_read_b32 v225, a1
	v_accvgpr_read_b32 v226, a2
	v_accvgpr_read_b32 v228, a3
	v_accvgpr_read_b32 v229, a4
	s_branch .Lrm_done_20
.Lrm_orig_20:
	global_store_dwordx4 v[98:99], v[88:91], off
.Lrm_done_20:
	v_pk_mul_f32 v[80:81], v[112:113], v[80:81]
	v_pk_mul_f32 v[82:83], v[82:83], v[96:97] op_sel_hi:[1,0]
	v_mov_b32_e32 v88, v169
	v_pk_mul_f32 v[78:79], v[78:79], v[88:89] op_sel_hi:[1,0]
	v_pk_mul_f32 v[76:77], v[76:77], v[88:89] op_sel_hi:[1,0]
	v_pk_mul_f32 v[90:91], v[78:79], v[78:79]
	v_pk_mul_f32 v[92:93], v[76:77], v[76:77]
	v_pk_mul_f32 v[68:69], v[68:69], v[88:89] op_sel_hi:[1,0]
	v_pk_mov_b32 v[94:95], v[92:93], v[90:91] op_sel:[1,0]
	v_mov_b32_e32 v93, v91
	v_pk_add_f32 v[90:91], v[94:95], v[92:93]
	v_pk_mul_f32 v[92:93], v[74:75], v[88:89] op_sel_hi:[1,0]
	v_pk_mul_f32 v[94:95], v[72:73], v[88:89] op_sel_hi:[1,0]
	v_pk_mul_f32 v[72:73], v[92:93], v[92:93]
	v_pk_mul_f32 v[74:75], v[94:95], v[94:95]
	v_pk_mul_f32 v[70:71], v[70:71], v[88:89] op_sel_hi:[1,0]
	v_pk_mov_b32 v[100:101], v[74:75], v[72:73] op_sel:[1,0]
	v_mov_b32_e32 v75, v73
	v_pk_add_f32 v[72:73], v[100:101], v[74:75]
	v_pk_add_f32 v[90:91], v[90:91], v[90:91] op_sel_hi:[0,1]
	v_pk_add_f32 v[72:73], v[72:73], v[72:73] op_sel_hi:[0,1]
	v_mul_f32_e32 v72, v68, v68
	v_pk_fma_f32 v[74:75], v[68:69], v[68:69], v[72:73] op_sel_hi:[1,1,0]
	v_mul_f32_e32 v72, v70, v70
	v_pk_fma_f32 v[100:101], v[70:71], v[70:71], v[72:73] op_sel_hi:[1,1,0]
	v_pk_mul_f32 v[66:67], v[66:67], v[88:89] op_sel_hi:[1,0]
	v_pk_mul_f32 v[64:65], v[64:65], v[88:89] op_sel_hi:[1,0]
	v_mul_f32_e32 v90, v66, v66
	v_mul_f32_e32 v74, v64, v64
	v_mul_f32_e32 v100, v65, v65
	v_mul_f32_e32 v72, v67, v67
	v_pk_add_f32 v[74:75], v[74:75], v[100:101]
	v_pk_add_f32 v[72:73], v[90:91], v[72:73]
	v_pk_mul_f32 v[82:83], v[114:115], v[82:83]
	v_pk_add_f32 v[72:73], v[74:75], v[72:73]
	v_pk_mul_f32 v[74:75], v[86:87], v[96:97] op_sel_hi:[1,0]
	v_add_f32_e32 v88, v72, v73
	ds_bpermute_b32 v89, v140, v88
	v_pk_mul_f32 v[72:73], v[84:85], v[96:97] op_sel_hi:[1,0]
	v_pk_mul_f32 v[74:75], v[118:119], v[74:75]
	v_pk_mul_f32 v[72:73], v[116:117], v[72:73]
	s_waitcnt lgkmcnt(0)
	v_add_f32_e32 v84, v88, v89
	ds_bpermute_b32 v85, v141, v84
	v_cvt_pk_bf16_f32 v72, v72, v73
	v_cvt_pk_bf16_f32 v73, v74, v75
	v_cvt_pk_bf16_f32 v74, v80, v81
	s_waitcnt lgkmcnt(0)
	v_add_f32_e32 v84, v84, v85
	v_fmamk_f32 v84, v84, 0x3c800000, v186
	v_mul_f32_e32 v85, 0x4f800000, v84
	v_cmp_gt_f32_e32 vcc, s50, v84
	s_nop 1
	v_cndmask_b32_e32 v84, v84, v85, vcc
	v_sqrt_f32_e32 v85, v84
	s_nop 0
	v_add_u32_e32 v75, -1, v85
	v_fma_f32 v80, -v75, v85, v84
	v_cmp_ge_f32_e64 s[4:5], 0, v80
	v_add_u32_e32 v80, 1, v85
	v_fma_f32 v81, -v80, v85, v84
	v_cndmask_b32_e64 v75, v85, v75, s[4:5]
	v_cmp_lt_f32_e64 s[4:5], 0, v81
	s_nop 1
	v_cndmask_b32_e64 v75, v75, v80, s[4:5]
	v_mul_f32_e32 v80, 0x37800000, v75
	v_cndmask_b32_e32 v75, v75, v80, vcc
	v_cmp_class_f32_e32 vcc, v84, v187
	s_nop 1
	v_cndmask_b32_e32 v80, v75, v84, vcc
	v_div_scale_f32 v81, s[0:1], v80, v80, 1.0
	v_rcp_f32_e32 v84, v81
	v_cvt_pk_bf16_f32 v75, v82, v83
	s_mov_b64 vcc, s[100:101]
	s_cbranch_vccz .Lrm_orig_21
	v_accvgpr_write_b32 a0, v224
	v_accvgpr_write_b32 a1, v225
	v_accvgpr_write_b32 a2, v226
	v_accvgpr_write_b32 a3, v228
	v_accvgpr_write_b32 a4, v229
	v_subrev_u32_e32 v224, s98, v98
	v_add_u32_e32 v224, 64, v224
	v_lshrrev_b32_e32 v225, 10, v224
	v_and_b32_e32 v226, 0x3ff, v224
	v_lshrrev_b32_e32 v228, 7, v226
	v_mul_u32_u24_e32 v228, 0x204000, v228
	v_and_b32_e32 v226, 0x70, v226
	v_lshl_add_u32 v228, v226, 5, v228
	v_add_u32_e32 v229, 0x80, v225
	v_and_b32_e32 v226, 0xff, v225
	v_cmp_gt_u32_e32 vcc, 16, v226
	v_and_b32_e32 v224, 63, v226
	v_add_u32_e32 v226, 0x70, v226
	s_nop 1
	v_cndmask_b32_e32 v224, v224, v226, vcc
	v_cmp_lt_u32_e32 vcc, 0x3fff, v225
	s_nop 2
	v_cndmask_b32_e32 v229, v229, v224, vcc
	v_lshrrev_b32_e32 v224, 5, v229
	v_lshl_add_u32 v228, v224, 12, v228
	v_and_b32_e32 v224, 31, v229
	v_lshl_add_u32 v228, v224, 4, v228
	v_mov_b32_e32 v229, 0
	v_lshl_add_u64 v[224:225], s[98:99], 0, v[228:229]
	v_lshl_add_u64 v[228:229], v[98:99], 0, 64
	v_cmp_ne_u32_e64 vcc, s100, 0
	s_nop 2
	v_cndmask_b32_e32 v224, v228, v224, vcc
	v_cndmask_b32_e32 v225, v229, v225, vcc
	global_store_dwordx4 v[224:225], v[72:75], off
	s_nop 1
	v_accvgpr_read_b32 v224, a0
	v_accvgpr_read_b32 v225, a1
	v_accvgpr_read_b32 v226, a2
	v_accvgpr_read_b32 v228, a3
	v_accvgpr_read_b32 v229, a4
	s_branch .Lrm_done_21
; __device__ __forceinline__ unsigned cvt_pk_bf16(float lo, float hi) { unsigned r; asm volatile("v_cvt_pk_bf16_f32 %0, %1, %2" : "=v"(r) : "v"(lo), "v"(hi)); return r; }
;     __device__ __forceinline__ void operator()(const f32x4 (&acc)[2][2][4][2], const Unit& u, int wr, int wc, int fr, int fq) const {
;     ...
;                 for (int m = 0; m < 4; ++m) { const int row = row0 + ai * HALF + m * 16; const float rs = rsv[ai][m]; float sq = 0.f; f32x4 t[2][2];
; #pragma unroll
;                     for (int bj = 0; bj < 2; ++bj)
; #pragma unroll
;                         for (int n = 0; n < 2; ++n) { t[bj][n] = acc[ai][bj][m][n] * rs; sq += (t[bj][n][0] * t[bj][n][0] + t[bj][n][1] * t[bj][n][1]) + (t[bj][n][2] * t[bj][n][2] + t[bj][n][3] * t[bj][n][3]); }
;                     sq += __shfl_xor(sq, 16); sq += __shfl_xor(sq, 32);
;                     const float rn = 1.0f / sqrtf(sq * (1.0f / 64.0f) + 1e-6f);
; #pragma unroll
;                     for (int bj = 0; bj < 2; ++bj) { const f32x4 a = t[bj][0] * rn * gv[bj][0], b = t[bj][1] * rn * gv[bj][1];
;                         u32x4 w; w.x = cvt_pk_bf16(a[0], a[1]); w.y = cvt_pk_bf16(a[2], a[3]); w.z = cvt_pk_bf16(b[0], b[1]); w.w = cvt_pk_bf16(b[2], b[3]);
;                         *(u32x4*)(dst + (size_t)row * 512 + head * 64 + 32 * bj + 8 * fq) = w; } }
.Lrm_orig_21:
	global_store_dwordx4 v[98:99], v[72:75], off offset:64
.Lrm_done_21:
	s_nop 1
	v_fma_f32 v73, -v81, v84, 1.0
	v_fmac_f32_e32 v84, v73, v84
	v_div_scale_f32 v73, vcc, 1.0, v80, 1.0
	v_mul_f32_e32 v74, v73, v84
	v_fma_f32 v75, -v81, v74, v73
	v_fmac_f32_e32 v74, v75, v84
	v_fma_f32 v73, -v81, v74, v73
	v_or_b32_e32 v72, 48, v166
	v_div_fmas_f32 v73, v73, v84, v74
	v_div_fixup_f32 v80, v73, v80, 1.0
	v_ashrrev_i32_e32 v73, 31, v72
	v_lshlrev_b64 v[72:73], 10, v[72:73]
	v_lshl_add_u64 v[82:83], v[130:131], 0, v[72:73]
	v_pk_mul_f32 v[72:73], v[76:77], v[80:81] op_sel_hi:[1,0]
	v_pk_mul_f32 v[74:75], v[78:79], v[80:81] op_sel_hi:[1,0]
	v_pk_mul_f32 v[76:77], v[94:95], v[80:81] op_sel_hi:[1,0]
	v_pk_mul_f32 v[78:79], v[92:93], v[80:81] op_sel_hi:[1,0]
	v_pk_mul_f32 v[74:75], v[126:127], v[74:75]
	v_pk_mul_f32 v[72:73], v[124:125], v[72:73]
	v_pk_mul_f32 v[78:79], v[122:123], v[78:79]
	v_pk_mul_f32 v[76:77], v[120:121], v[76:77]
	v_cvt_pk_bf16_f32 v72, v72, v73
	v_cvt_pk_bf16_f32 v73, v74, v75
	v_pk_mul_f32 v[64:65], v[64:65], v[80:81] op_sel_hi:[1,0]
	v_cvt_pk_bf16_f32 v74, v76, v77
	v_cvt_pk_bf16_f32 v75, v78, v79
	v_pk_mul_f32 v[76:77], v[62:63], v[62:63]
	v_pk_mul_f32 v[78:79], v[60:61], v[60:61]
	s_mov_b64 vcc, s[100:101]
	s_cbranch_vccz .Lrm_orig_22
	v_accvgpr_write_b32 a0, v224
	v_accvgpr_write_b32 a1, v225
	v_accvgpr_write_b32 a2, v226
	v_accvgpr_write_b32 a3, v228
	v_accvgpr_write_b32 a4, v229
	v_subrev_u32_e32 v224, s98, v82
	v_lshrrev_b32_e32 v225, 10, v224
	v_and_b32_e32 v226, 0x3ff, v224
	v_lshrrev_b32_e32 v228, 7, v226
	v_mul_u32_u24_e32 v228, 0x204000, v228
	v_and_b32_e32 v226, 0x70, v226
	v_lshl_add_u32 v228, v226, 5, v228
	v_add_u32_e32 v229, 0x80, v225
	v_and_b32_e32 v226, 0xff, v225
	v_cmp_gt_u32_e32 vcc, 16, v226
	v_and_b32_e32 v224, 63, v226
	v_add_u32_e32 v226, 0x70, v226
	s_nop 1
	v_cndmask_b32_e32 v224, v224, v226, vcc
	v_cmp_lt_u32_e32 vcc, 0x3fff, v225
	s_nop 2
	v_cndmask_b32_e32 v229, v229, v224, vcc
	v_lshrrev_b32_e32 v224, 5, v229
	v_lshl_add_u32 v228, v224, 12, v228
	v_and_b32_e32 v224, 31, v229
	v_lshl_add_u32 v228, v224, 4, v228
	v_mov_b32_e32 v229, 0
	v_lshl_add_u64 v[224:225], s[98:99], 0, v[228:229]
	v_cmp_ne_u32_e64 vcc, s100, 0
	s_nop 2
	v_cndmask_b32_e32 v224, v82, v224, vcc
	v_cndmask_b32_e32 v225, v83, v225, vcc
	global_store_dwordx4 v[224:225], v[72:75], off
	s_nop 1
	v_accvgpr_read_b32 v224, a0
	v_accvgpr_read_b32 v225, a1
	v_accvgpr_read_b32 v226, a2
	v_accvgpr_read_b32 v228, a3
	v_accvgpr_read_b32 v229, a4
	s_branch .Lrm_done_22
.Lrm_orig_22:
	global_store_dwordx4 v[82:83], v[72:75], off
.Lrm_done_22:
	v_pk_mov_b32 v[84:85], v[78:79], v[76:77] op_sel:[1,0]
	v_mov_b32_e32 v79, v77
	v_pk_add_f32 v[76:77], v[84:85], v[78:79]
	v_pk_mul_f32 v[78:79], v[58:59], v[164:165] op_sel_hi:[1,0]
	v_pk_mul_f32 v[84:85], v[56:57], v[164:165] op_sel_hi:[1,0]
	v_pk_mul_f32 v[56:57], v[78:79], v[78:79]
	v_pk_mul_f32 v[58:59], v[84:85], v[84:85]
	v_pk_add_f32 v[76:77], v[76:77], v[76:77] op_sel_hi:[0,1]
	v_pk_mov_b32 v[86:87], v[58:59], v[56:57] op_sel:[1,0]
	v_mov_b32_e32 v59, v57
	v_pk_add_f32 v[56:57], v[86:87], v[58:59]
	v_mul_f32_e32 v76, v50, v50
	v_pk_add_f32 v[56:57], v[56:57], v[56:57] op_sel_hi:[0,1]
	v_mul_f32_e32 v56, v52, v52
	v_pk_fma_f32 v[58:59], v[52:53], v[52:53], v[56:57] op_sel_hi:[1,1,0]
	v_mul_f32_e32 v56, v54, v54
	v_pk_fma_f32 v[86:87], v[54:55], v[54:55], v[56:57] op_sel_hi:[1,1,0]
	v_mul_f32_e32 v58, v48, v48
	v_mul_f32_e32 v86, v49, v49
	v_mul_f32_e32 v56, v51, v51
	v_pk_add_f32 v[58:59], v[58:59], v[86:87]
	v_pk_add_f32 v[56:57], v[76:77], v[56:57]
	v_pk_mul_f32 v[66:67], v[66:67], v[80:81] op_sel_hi:[1,0]
	v_pk_add_f32 v[56:57], v[58:59], v[56:57]
	v_pk_mul_f32 v[58:59], v[70:71], v[80:81] op_sel_hi:[1,0]
	v_add_f32_e32 v76, v56, v57
	ds_bpermute_b32 v77, v140, v76
	v_pk_mul_f32 v[56:57], v[68:69], v[80:81] op_sel_hi:[1,0]
	v_pk_mul_f32 v[58:59], v[118:119], v[58:59]
	v_pk_mul_f32 v[56:57], v[116:117], v[56:57]
	v_pk_mul_f32 v[66:67], v[114:115], v[66:67]
	s_waitcnt lgkmcnt(0)
	v_add_f32_e32 v68, v76, v77
	ds_bpermute_b32 v69, v141, v68
	v_cvt_pk_bf16_f32 v56, v56, v57
	v_cvt_pk_bf16_f32 v57, v58, v59
	v_pk_mul_f32 v[64:65], v[112:113], v[64:65]
	s_waitcnt lgkmcnt(0)
	v_add_f32_e32 v68, v68, v69
	v_fmamk_f32 v68, v68, 0x3c800000, v186
	v_mul_f32_e32 v69, 0x4f800000, v68
	v_cmp_gt_f32_e32 vcc, s50, v68
	s_nop 1
	v_cndmask_b32_e32 v68, v68, v69, vcc
	v_sqrt_f32_e32 v69, v68
	s_nop 0
	v_add_u32_e32 v58, -1, v69
	v_fma_f32 v59, -v58, v69, v68
	v_cmp_ge_f32_e64 s[4:5], 0, v59
	v_add_u32_e32 v59, 1, v69
	s_nop 0
	v_cndmask_b32_e64 v58, v69, v58, s[4:5]
	v_fma_f32 v69, -v59, v69, v68
	v_cmp_lt_f32_e64 s[4:5], 0, v69
	s_nop 1
	v_cndmask_b32_e64 v58, v58, v59, s[4:5]
	v_mul_f32_e32 v59, 0x37800000, v58
	v_cndmask_b32_e32 v58, v58, v59, vcc
	v_cmp_class_f32_e32 vcc, v68, v187
	s_nop 1
	v_cndmask_b32_e32 v68, v58, v68, vcc
	v_div_scale_f32 v69, s[0:1], v68, v68, 1.0
	v_rcp_f32_e32 v70, v69
	v_cvt_pk_bf16_f32 v58, v64, v65
	v_cvt_pk_bf16_f32 v59, v66, v67
	s_mov_b64 vcc, s[100:101]
	s_cbranch_vccz .Lrm_orig_23
	v_accvgpr_write_b32 a0, v224
	v_accvgpr_write_b32 a1, v225
	v_accvgpr_write_b32 a2, v226
	v_accvgpr_write_b32 a3, v228
	v_accvgpr_write_b32 a4, v229
	v_subrev_u32_e32 v224, s98, v82
	v_add_u32_e32 v224, 64, v224
	v_lshrrev_b32_e32 v225, 10, v224
	v_and_b32_e32 v226, 0x3ff, v224
	v_lshrrev_b32_e32 v228, 7, v226
	v_mul_u32_u24_e32 v228, 0x204000, v228
	v_and_b32_e32 v226, 0x70, v226
	v_lshl_add_u32 v228, v226, 5, v228
	v_add_u32_e32 v229, 0x80, v225
	v_and_b32_e32 v226, 0xff, v225
	v_cmp_gt_u32_e32 vcc, 16, v226
	v_and_b32_e32 v224, 63, v226
	v_add_u32_e32 v226, 0x70, v226
	s_nop 1
	v_cndmask_b32_e32 v224, v224, v226, vcc
	v_cmp_lt_u32_e32 vcc, 0x3fff, v225
	s_nop 2
	v_cndmask_b32_e32 v229, v229, v224, vcc
	v_lshrrev_b32_e32 v224, 5, v229
	v_lshl_add_u32 v228, v224, 12, v228
	v_and_b32_e32 v224, 31, v229
	v_lshl_add_u32 v228, v224, 4, v228
	v_mov_b32_e32 v229, 0
	v_lshl_add_u64 v[224:225], s[98:99], 0, v[228:229]
	v_lshl_add_u64 v[228:229], v[82:83], 0, 64
	v_cmp_ne_u32_e64 vcc, s100, 0
	s_nop 2
	v_cndmask_b32_e32 v224, v228, v224, vcc
	v_cndmask_b32_e32 v225, v229, v225, vcc
	global_store_dwordx4 v[224:225], v[56:59], off
	s_nop 1
	v_accvgpr_read_b32 v224, a0
	v_accvgpr_read_b32 v225, a1
	v_accvgpr_read_b32 v226, a2
	v_accvgpr_read_b32 v228, a3
	v_accvgpr_read_b32 v229, a4
	s_branch .Lrm_done_23
; __device__ __forceinline__ unsigned cvt_pk_bf16(float lo, float hi) { unsigned r; asm volatile("v_cvt_pk_bf16_f32 %0, %1, %2" : "=v"(r) : "v"(lo), "v"(hi)); return r; }
;     __device__ __forceinline__ void operator()(const f32x4 (&acc)[2][2][4][2], const Unit& u, int wr, int wc, int fr, int fq) const {
;     ...
;                 for (int m = 0; m < 4; ++m) { const int row = row0 + ai * HALF + m * 16; const float rs = rsv[ai][m]; float sq = 0.f; f32x4 t[2][2];
; #pragma unroll
;                     for (int bj = 0; bj < 2; ++bj)
; #pragma unroll
;                         for (int n = 0; n < 2; ++n) { t[bj][n] = acc[ai][bj][m][n] * rs; sq += (t[bj][n][0] * t[bj][n][0] + t[bj][n][1] * t[bj][n][1]) + (t[bj][n][2] * t[bj][n][2] + t[bj][n][3] * t[bj][n][3]); }
;                     sq += __shfl_xor(sq, 16); sq += __shfl_xor(sq, 32);
;                     const float rn = 1.0f / sqrtf(sq * (1.0f / 64.0f) + 1e-6f);
; #pragma unroll
;                     for (int bj = 0; bj < 2; ++bj) { const f32x4 a = t[bj][0] * rn * gv[bj][0], b = t[bj][1] * rn * gv[bj][1];
;                         u32x4 w; w.x = cvt_pk_bf16(a[0], a[1]); w.y = cvt_pk_bf16(a[2], a[3]); w.z = cvt_pk_bf16(b[0], b[1]); w.w = cvt_pk_bf16(b[2], b[3]);
;                         *(u32x4*)(dst + (size_t)row * 512 + head * 64 + 32 * bj + 8 * fq) = w; } }
.Lrm_orig_23:
	global_store_dwordx4 v[82:83], v[56:59], off offset:64
.Lrm_done_23:
	s_mov_b64 s[0:1], 0x20000
	v_lshl_add_u64 v[66:67], v[128:129], 0, s[0:1]
	v_fma_f32 v56, -v69, v70, 1.0
	v_fmac_f32_e32 v70, v56, v70
	v_div_scale_f32 v56, vcc, 1.0, v68, 1.0
	v_mul_f32_e32 v57, v56, v70
	v_fma_f32 v58, -v69, v57, v56
	v_fmac_f32_e32 v57, v58, v70
	v_fma_f32 v56, -v69, v57, v56
	v_div_fmas_f32 v56, v56, v70, v57
	v_div_fixup_f32 v64, v56, v68, 1.0
	v_pk_mul_f32 v[56:57], v[60:61], v[64:65] op_sel_hi:[1,0]
	v_pk_mul_f32 v[58:59], v[62:63], v[64:65] op_sel_hi:[1,0]
	v_pk_mul_f32 v[62:63], v[78:79], v[64:65] op_sel_hi:[1,0]
	v_pk_mul_f32 v[58:59], v[126:127], v[58:59]
	v_pk_mul_f32 v[56:57], v[124:125], v[56:57]
	v_pk_mul_f32 v[60:61], v[84:85], v[64:65] op_sel_hi:[1,0]
	v_pk_mul_f32 v[62:63], v[122:123], v[62:63]
	v_pk_mul_f32 v[60:61], v[120:121], v[60:61]
	v_cvt_pk_bf16_f32 v56, v56, v57
	v_cvt_pk_bf16_f32 v57, v58, v59
	s_mov_b32 s0, 0x20000
	v_cvt_pk_bf16_f32 v58, v60, v61
	v_cvt_pk_bf16_f32 v59, v62, v63
	v_mov_b32_e32 v62, v165
	v_pk_mul_f32 v[46:47], v[46:47], v[62:63] op_sel_hi:[1,0]
	v_pk_mul_f32 v[44:45], v[44:45], v[62:63] op_sel_hi:[1,0]
	v_pk_mul_f32 v[68:69], v[46:47], v[46:47]
	v_pk_mul_f32 v[70:71], v[44:45], v[44:45]
	v_pk_mul_f32 v[36:37], v[36:37], v[62:63] op_sel_hi:[1,0]
	v_pk_mov_b32 v[72:73], v[70:71], v[68:69] op_sel:[1,0]
	v_mov_b32_e32 v71, v69
	v_pk_add_f32 v[68:69], v[72:73], v[70:71]
	v_pk_mul_f32 v[70:71], v[42:43], v[62:63] op_sel_hi:[1,0]
	v_pk_mul_f32 v[72:73], v[40:41], v[62:63] op_sel_hi:[1,0]
	v_pk_mul_f32 v[40:41], v[70:71], v[70:71]
	v_pk_mul_f32 v[42:43], v[72:73], v[72:73]
	v_pk_mul_f32 v[38:39], v[38:39], v[62:63] op_sel_hi:[1,0]
	v_pk_mov_b32 v[74:75], v[42:43], v[40:41] op_sel:[1,0]
	v_mov_b32_e32 v43, v41
	v_pk_add_f32 v[40:41], v[74:75], v[42:43]
	v_pk_add_f32 v[68:69], v[68:69], v[68:69] op_sel_hi:[0,1]
	v_pk_add_f32 v[40:41], v[40:41], v[40:41] op_sel_hi:[0,1]
	v_mul_f32_e32 v40, v36, v36
	v_pk_fma_f32 v[42:43], v[36:37], v[36:37], v[40:41] op_sel_hi:[1,1,0]
	v_mul_f32_e32 v40, v38, v38
	v_pk_fma_f32 v[74:75], v[38:39], v[38:39], v[40:41] op_sel_hi:[1,1,0]
	v_pk_mul_f32 v[34:35], v[34:35], v[62:63] op_sel_hi:[1,0]
	v_pk_mul_f32 v[32:33], v[32:33], v[62:63] op_sel_hi:[1,0]
	v_mul_f32_e32 v68, v34, v34
	v_mul_f32_e32 v42, v32, v32
	v_mul_f32_e32 v74, v33, v33
	v_mul_f32_e32 v40, v35, v35
	v_pk_add_f32 v[42:43], v[42:43], v[74:75]
	v_pk_add_f32 v[40:41], v[68:69], v[40:41]
	v_add_co_u32_e32 v60, vcc, s0, v128
	v_pk_add_f32 v[40:41], v[42:43], v[40:41]
	s_nop 0
	v_addc_co_u32_e32 v61, vcc, 0, v129, vcc
	v_add_f32_e32 v62, v40, v41
	ds_bpermute_b32 v63, v140, v62
	v_pk_mul_f32 v[40:41], v[52:53], v[64:65] op_sel_hi:[1,0]
	v_pk_mul_f32 v[42:43], v[54:55], v[64:65] op_sel_hi:[1,0]
	v_pk_mul_f32 v[40:41], v[116:117], v[40:41]
	v_pk_mul_f32 v[42:43], v[118:119], v[42:43]
	s_waitcnt lgkmcnt(0)
	v_add_f32_e32 v52, v62, v63
	ds_bpermute_b32 v53, v141, v52
	s_mov_b64 vcc, s[100:101]
	s_cbranch_vccz .Lrm_orig_24
	v_accvgpr_write_b32 a0, v224
	v_accvgpr_write_b32 a1, v225
	v_accvgpr_write_b32 a2, v226
	v_accvgpr_write_b32 a3, v228
	v_accvgpr_write_b32 a4, v229
	v_subrev_u32_e32 v224, s98, v60
	v_lshrrev_b32_e32 v225, 10, v224
	v_and_b32_e32 v226, 0x3ff, v224
	v_lshrrev_b32_e32 v228, 7, v226
	v_mul_u32_u24_e32 v228, 0x204000, v228
	v_and_b32_e32 v226, 0x70, v226
	v_lshl_add_u32 v228, v226, 5, v228
	v_add_u32_e32 v229, 0x80, v225
	v_and_b32_e32 v226, 0xff, v225
	v_cmp_gt_u32_e32 vcc, 16, v226
	v_and_b32_e32 v224, 63, v226
	v_add_u32_e32 v226, 0x70, v226
	s_nop 1
	v_cndmask_b32_e32 v224, v224, v226, vcc
	v_cmp_lt_u32_e32 vcc, 0x3fff, v225
	s_nop 2
	v_cndmask_b32_e32 v229, v229, v224, vcc
	v_lshrrev_b32_e32 v224, 5, v229
	v_lshl_add_u32 v228, v224, 12, v228
	v_and_b32_e32 v224, 31, v229
	v_lshl_add_u32 v228, v224, 4, v228
	v_mov_b32_e32 v229, 0
	v_lshl_add_u64 v[224:225], s[98:99], 0, v[228:229]
	v_cmp_ne_u32_e64 vcc, s100, 0
	s_nop 2
	v_cndmask_b32_e32 v224, v60, v224, vcc
	v_cndmask_b32_e32 v225, v61, v225, vcc
	global_store_dwordx4 v[224:225], v[56:59], off
	s_nop 1
	v_accvgpr_read_b32 v224, a0
	v_accvgpr_read_b32 v225, a1
	v_accvgpr_read_b32 v226, a2
	v_accvgpr_read_b32 v228, a3
	v_accvgpr_read_b32 v229, a4
	s_branch .Lrm_done_24
.Lrm_orig_24:
	global_store_dwordx4 v[60:61], v[56:59], off
.Lrm_done_24:
	v_cvt_pk_bf16_f32 v40, v40, v41
	v_cvt_pk_bf16_f32 v41, v42, v43
	v_pk_mul_f32 v[48:49], v[48:49], v[64:65] op_sel_hi:[1,0]
	s_waitcnt lgkmcnt(0)
	v_add_f32_e32 v52, v52, v53
	v_fmamk_f32 v52, v52, 0x3c800000, v186
	v_mul_f32_e32 v53, 0x4f800000, v52
	v_cmp_gt_f32_e32 vcc, s50, v52
	v_pk_mul_f32 v[50:51], v[50:51], v[64:65] op_sel_hi:[1,0]
	v_pk_mul_f32 v[48:49], v[112:113], v[48:49]
	v_cndmask_b32_e32 v52, v52, v53, vcc
	v_sqrt_f32_e32 v53, v52
	v_pk_mul_f32 v[50:51], v[114:115], v[50:51]
	v_add_u32_e32 v42, -1, v53
	v_fma_f32 v43, -v42, v53, v52
	v_cmp_ge_f32_e64 s[4:5], 0, v43
	v_add_u32_e32 v43, 1, v53
	s_nop 0
	v_cndmask_b32_e64 v42, v53, v42, s[4:5]
	v_fma_f32 v53, -v43, v53, v52
	v_cmp_lt_f32_e64 s[4:5], 0, v53
	s_nop 1
	v_cndmask_b32_e64 v42, v42, v43, s[4:5]
	v_mul_f32_e32 v43, 0x37800000, v42
	v_cndmask_b32_e32 v42, v42, v43, vcc
	v_cmp_class_f32_e32 vcc, v52, v187
	s_nop 1
	v_cndmask_b32_e32 v52, v42, v52, vcc
	v_div_scale_f32 v53, s[0:1], v52, v52, 1.0
	v_rcp_f32_e32 v54, v53
	v_cvt_pk_bf16_f32 v42, v48, v49
	v_cvt_pk_bf16_f32 v43, v50, v51
	s_mov_b64 vcc, s[100:101]
	s_cbranch_vccz .Lrm_orig_25
	v_accvgpr_write_b32 a0, v224
	v_accvgpr_write_b32 a1, v225
	v_accvgpr_write_b32 a2, v226
	v_accvgpr_write_b32 a3, v228
	v_accvgpr_write_b32 a4, v229
	v_subrev_u32_e32 v224, s98, v66
	v_add_u32_e32 v224, 64, v224
	v_lshrrev_b32_e32 v225, 10, v224
	v_and_b32_e32 v226, 0x3ff, v224
	v_lshrrev_b32_e32 v228, 7, v226
	v_mul_u32_u24_e32 v228, 0x204000, v228
	v_and_b32_e32 v226, 0x70, v226
	v_lshl_add_u32 v228, v226, 5, v228
	v_add_u32_e32 v229, 0x80, v225
	v_and_b32_e32 v226, 0xff, v225
	v_cmp_gt_u32_e32 vcc, 16, v226
	v_and_b32_e32 v224, 63, v226
	v_add_u32_e32 v226, 0x70, v226
	s_nop 1
	v_cndmask_b32_e32 v224, v224, v226, vcc
	v_cmp_lt_u32_e32 vcc, 0x3fff, v225
	s_nop 2
	v_cndmask_b32_e32 v229, v229, v224, vcc
	v_lshrrev_b32_e32 v224, 5, v229
	v_lshl_add_u32 v228, v224, 12, v228
	v_and_b32_e32 v224, 31, v229
	v_lshl_add_u32 v228, v224, 4, v228
	v_mov_b32_e32 v229, 0
	v_lshl_add_u64 v[224:225], s[98:99], 0, v[228:229]
	v_lshl_add_u64 v[228:229], v[66:67], 0, 64
	v_cmp_ne_u32_e64 vcc, s100, 0
	s_nop 2
	v_cndmask_b32_e32 v224, v228, v224, vcc
	v_cndmask_b32_e32 v225, v229, v225, vcc
	global_store_dwordx4 v[224:225], v[40:43], off
	s_nop 1
	v_accvgpr_read_b32 v224, a0
	v_accvgpr_read_b32 v225, a1
	v_accvgpr_read_b32 v226, a2
	v_accvgpr_read_b32 v228, a3
	v_accvgpr_read_b32 v229, a4
	s_branch .Lrm_done_25
; __device__ __forceinline__ unsigned cvt_pk_bf16(float lo, float hi) { unsigned r; asm volatile("v_cvt_pk_bf16_f32 %0, %1, %2" : "=v"(r) : "v"(lo), "v"(hi)); return r; }
;     __device__ __forceinline__ void operator()(const f32x4 (&acc)[2][2][4][2], const Unit& u, int wr, int wc, int fr, int fq) const {
;     ...
;                 for (int m = 0; m < 4; ++m) { const int row = row0 + ai * HALF + m * 16; const float rs = rsv[ai][m]; float sq = 0.f; f32x4 t[2][2];
; #pragma unroll
;                     for (int bj = 0; bj < 2; ++bj)
; #pragma unroll
;                         for (int n = 0; n < 2; ++n) { t[bj][n] = acc[ai][bj][m][n] * rs; sq += (t[bj][n][0] * t[bj][n][0] + t[bj][n][1] * t[bj][n][1]) + (t[bj][n][2] * t[bj][n][2] + t[bj][n][3] * t[bj][n][3]); }
;                     sq += __shfl_xor(sq, 16); sq += __shfl_xor(sq, 32);
;                     const float rn = 1.0f / sqrtf(sq * (1.0f / 64.0f) + 1e-6f);
; #pragma unroll
;                     for (int bj = 0; bj < 2; ++bj) { const f32x4 a = t[bj][0] * rn * gv[bj][0], b = t[bj][1] * rn * gv[bj][1];
;                         u32x4 w; w.x = cvt_pk_bf16(a[0], a[1]); w.y = cvt_pk_bf16(a[2], a[3]); w.z = cvt_pk_bf16(b[0], b[1]); w.w = cvt_pk_bf16(b[2], b[3]);
;                         *(u32x4*)(dst + (size_t)row * 512 + head * 64 + 32 * bj + 8 * fq) = w; } }
.Lrm_orig_25:
	global_store_dwordx4 v[66:67], v[40:43], off offset:64
.Lrm_done_25:
	s_mov_b64 s[0:1], 0x24000
	v_lshl_add_u64 v[50:51], v[128:129], 0, s[0:1]
	v_fma_f32 v40, -v53, v54, 1.0
	v_fmac_f32_e32 v54, v40, v54
	v_div_scale_f32 v40, vcc, 1.0, v52, 1.0
	v_mul_f32_e32 v41, v40, v54
	v_fma_f32 v42, -v53, v41, v40
	v_fmac_f32_e32 v41, v42, v54
	v_fma_f32 v40, -v53, v41, v40
	v_div_fmas_f32 v40, v40, v54, v41
	v_div_fixup_f32 v48, v40, v52, 1.0
	v_pk_mul_f32 v[40:41], v[44:45], v[48:49] op_sel_hi:[1,0]
	v_pk_mul_f32 v[42:43], v[46:47], v[48:49] op_sel_hi:[1,0]
	v_pk_mul_f32 v[46:47], v[70:71], v[48:49] op_sel_hi:[1,0]
	v_pk_mul_f32 v[42:43], v[126:127], v[42:43]
	v_pk_mul_f32 v[40:41], v[124:125], v[40:41]
	v_pk_mul_f32 v[44:45], v[72:73], v[48:49] op_sel_hi:[1,0]
	v_pk_mul_f32 v[46:47], v[122:123], v[46:47]
	v_pk_mul_f32 v[44:45], v[120:121], v[44:45]
	v_cvt_pk_bf16_f32 v40, v40, v41
	v_cvt_pk_bf16_f32 v41, v42, v43
	v_pk_mul_f32 v[52:53], v[28:29], v[28:29]
	v_cvt_pk_bf16_f32 v42, v44, v45
	v_cvt_pk_bf16_f32 v43, v46, v47
	v_pk_mul_f32 v[46:47], v[30:31], v[30:31]
	s_mov_b32 s0, 0x24000
	v_pk_mov_b32 v[54:55], v[52:53], v[46:47] op_sel:[1,0]
	v_mov_b32_e32 v53, v47
	v_pk_add_f32 v[46:47], v[54:55], v[52:53]
	v_pk_mul_f32 v[52:53], v[26:27], v[162:163] op_sel_hi:[1,0]
	v_pk_mul_f32 v[54:55], v[24:25], v[162:163] op_sel_hi:[1,0]
	v_pk_mul_f32 v[24:25], v[52:53], v[52:53]
	v_pk_mul_f32 v[26:27], v[54:55], v[54:55]
	v_pk_add_f32 v[46:47], v[46:47], v[46:47] op_sel_hi:[0,1]
	v_pk_mov_b32 v[56:57], v[26:27], v[24:25] op_sel:[1,0]
	v_mov_b32_e32 v27, v25
	v_pk_add_f32 v[24:25], v[56:57], v[26:27]
	v_mul_f32_e32 v46, v18, v18
	v_pk_add_f32 v[24:25], v[24:25], v[24:25] op_sel_hi:[0,1]
	v_mul_f32_e32 v24, v20, v20
	v_pk_fma_f32 v[26:27], v[20:21], v[20:21], v[24:25] op_sel_hi:[1,1,0]
	v_mul_f32_e32 v24, v22, v22
	v_pk_fma_f32 v[56:57], v[22:23], v[22:23], v[24:25] op_sel_hi:[1,1,0]
	v_mul_f32_e32 v26, v16, v16
	v_mul_f32_e32 v56, v17, v17
	v_mul_f32_e32 v24, v19, v19
	v_pk_add_f32 v[26:27], v[26:27], v[56:57]
	v_pk_add_f32 v[24:25], v[46:47], v[24:25]
	v_add_co_u32_e32 v44, vcc, s0, v128
	v_pk_add_f32 v[24:25], v[26:27], v[24:25]
	s_nop 0
	v_addc_co_u32_e32 v45, vcc, 0, v129, vcc
	v_add_f32_e32 v46, v24, v25
	ds_bpermute_b32 v47, v140, v46
	v_pk_mul_f32 v[24:25], v[36:37], v[48:49] op_sel_hi:[1,0]
	v_pk_mul_f32 v[26:27], v[38:39], v[48:49] op_sel_hi:[1,0]
	v_pk_mul_f32 v[24:25], v[116:117], v[24:25]
	v_pk_mul_f32 v[26:27], v[118:119], v[26:27]
	s_waitcnt lgkmcnt(0)
	v_add_f32_e32 v36, v46, v47
	ds_bpermute_b32 v37, v141, v36
	s_mov_b64 vcc, s[100:101]
	s_cbranch_vccz .Lrm_orig_26
	v_accvgpr_write_b32 a0, v224
	v_accvgpr_write_b32 a1, v225
	v_accvgpr_write_b32 a2, v226
	v_accvgpr_write_b32 a3, v228
	v_accvgpr_write_b32 a4, v229
	v_subrev_u32_e32 v224, s98, v44
	v_lshrrev_b32_e32 v225, 10, v224
	v_and_b32_e32 v226, 0x3ff, v224
	v_lshrrev_b32_e32 v228, 7, v226
	v_mul_u32_u24_e32 v228, 0x204000, v228
	v_and_b32_e32 v226, 0x70, v226
	v_lshl_add_u32 v228, v226, 5, v228
	v_add_u32_e32 v229, 0x80, v225
	v_and_b32_e32 v226, 0xff, v225
	v_cmp_gt_u32_e32 vcc, 16, v226
	v_and_b32_e32 v224, 63, v226
	v_add_u32_e32 v226, 0x70, v226
	s_nop 1
	v_cndmask_b32_e32 v224, v224, v226, vcc
	v_cmp_lt_u32_e32 vcc, 0x3fff, v225
	s_nop 2
	v_cndmask_b32_e32 v229, v229, v224, vcc
	v_lshrrev_b32_e32 v224, 5, v229
	v_lshl_add_u32 v228, v224, 12, v228
	v_and_b32_e32 v224, 31, v229
	v_lshl_add_u32 v228, v224, 4, v228
	v_mov_b32_e32 v229, 0
	v_lshl_add_u64 v[224:225], s[98:99], 0, v[228:229]
	v_cmp_ne_u32_e64 vcc, s100, 0
	s_nop 2
	v_cndmask_b32_e32 v224, v44, v224, vcc
	v_cndmask_b32_e32 v225, v45, v225, vcc
	global_store_dwordx4 v[224:225], v[40:43], off
	s_nop 1
	v_accvgpr_read_b32 v224, a0
	v_accvgpr_read_b32 v225, a1
	v_accvgpr_read_b32 v226, a2
	v_accvgpr_read_b32 v228, a3
	v_accvgpr_read_b32 v229, a4
	s_branch .Lrm_done_26
.Lrm_orig_26:
	global_store_dwordx4 v[44:45], v[40:43], off
.Lrm_done_26:
	v_cvt_pk_bf16_f32 v24, v24, v25
	v_cvt_pk_bf16_f32 v25, v26, v27
	v_pk_mul_f32 v[32:33], v[32:33], v[48:49] op_sel_hi:[1,0]
	s_waitcnt lgkmcnt(0)
	v_add_f32_e32 v36, v36, v37
	v_fmamk_f32 v36, v36, 0x3c800000, v186
	v_mul_f32_e32 v37, 0x4f800000, v36
	v_cmp_gt_f32_e32 vcc, s50, v36
	v_pk_mul_f32 v[34:35], v[34:35], v[48:49] op_sel_hi:[1,0]
	v_pk_mul_f32 v[32:33], v[112:113], v[32:33]
	v_cndmask_b32_e32 v36, v36, v37, vcc
	v_sqrt_f32_e32 v37, v36
	v_pk_mul_f32 v[34:35], v[114:115], v[34:35]
	v_add_u32_e32 v26, -1, v37
	v_fma_f32 v27, -v26, v37, v36
	v_cmp_ge_f32_e64 s[4:5], 0, v27
	v_add_u32_e32 v27, 1, v37
	s_nop 0
	v_cndmask_b32_e64 v26, v37, v26, s[4:5]
	v_fma_f32 v37, -v27, v37, v36
	v_cmp_lt_f32_e64 s[4:5], 0, v37
	s_nop 1
	v_cndmask_b32_e64 v26, v26, v27, s[4:5]
	v_mul_f32_e32 v27, 0x37800000, v26
	v_cndmask_b32_e32 v26, v26, v27, vcc
	v_cmp_class_f32_e32 vcc, v36, v187
	s_nop 1
	v_cndmask_b32_e32 v36, v26, v36, vcc
	v_div_scale_f32 v37, s[0:1], v36, v36, 1.0
	v_rcp_f32_e32 v38, v37
	v_cvt_pk_bf16_f32 v26, v32, v33
	v_cvt_pk_bf16_f32 v27, v34, v35
	s_mov_b64 vcc, s[100:101]
	s_cbranch_vccz .Lrm_orig_27
	v_accvgpr_write_b32 a0, v224
	v_accvgpr_write_b32 a1, v225
	v_accvgpr_write_b32 a2, v226
	v_accvgpr_write_b32 a3, v228
	v_accvgpr_write_b32 a4, v229
	v_subrev_u32_e32 v224, s98, v50
	v_add_u32_e32 v224, 64, v224
	v_lshrrev_b32_e32 v225, 10, v224
	v_and_b32_e32 v226, 0x3ff, v224
	v_lshrrev_b32_e32 v228, 7, v226
	v_mul_u32_u24_e32 v228, 0x204000, v228
	v_and_b32_e32 v226, 0x70, v226
	v_lshl_add_u32 v228, v226, 5, v228
	v_add_u32_e32 v229, 0x80, v225
	v_and_b32_e32 v226, 0xff, v225
	v_cmp_gt_u32_e32 vcc, 16, v226
	v_and_b32_e32 v224, 63, v226
	v_add_u32_e32 v226, 0x70, v226
	s_nop 1
	v_cndmask_b32_e32 v224, v224, v226, vcc
	v_cmp_lt_u32_e32 vcc, 0x3fff, v225
	s_nop 2
	v_cndmask_b32_e32 v229, v229, v224, vcc
	v_lshrrev_b32_e32 v224, 5, v229
	v_lshl_add_u32 v228, v224, 12, v228
	v_and_b32_e32 v224, 31, v229
	v_lshl_add_u32 v228, v224, 4, v228
	v_mov_b32_e32 v229, 0
	v_lshl_add_u64 v[224:225], s[98:99], 0, v[228:229]
	v_lshl_add_u64 v[228:229], v[50:51], 0, 64
	v_cmp_ne_u32_e64 vcc, s100, 0
	s_nop 2
	v_cndmask_b32_e32 v224, v228, v224, vcc
	v_cndmask_b32_e32 v225, v229, v225, vcc
	global_store_dwordx4 v[224:225], v[24:27], off
	s_nop 1
	v_accvgpr_read_b32 v224, a0
	v_accvgpr_read_b32 v225, a1
	v_accvgpr_read_b32 v226, a2
	v_accvgpr_read_b32 v228, a3
	v_accvgpr_read_b32 v229, a4
	s_branch .Lrm_done_27
; __device__ __forceinline__ unsigned cvt_pk_bf16(float lo, float hi) { unsigned r; asm volatile("v_cvt_pk_bf16_f32 %0, %1, %2" : "=v"(r) : "v"(lo), "v"(hi)); return r; }
;     __device__ __forceinline__ void operator()(const f32x4 (&acc)[2][2][4][2], const Unit& u, int wr, int wc, int fr, int fq) const {
;     ...
;                 for (int m = 0; m < 4; ++m) { const int row = row0 + ai * HALF + m * 16; const float rs = rsv[ai][m]; float sq = 0.f; f32x4 t[2][2];
; #pragma unroll
;                     for (int bj = 0; bj < 2; ++bj)
; #pragma unroll
;                         for (int n = 0; n < 2; ++n) { t[bj][n] = acc[ai][bj][m][n] * rs; sq += (t[bj][n][0] * t[bj][n][0] + t[bj][n][1] * t[bj][n][1]) + (t[bj][n][2] * t[bj][n][2] + t[bj][n][3] * t[bj][n][3]); }
;                     sq += __shfl_xor(sq, 16); sq += __shfl_xor(sq, 32);
;                     const float rn = 1.0f / sqrtf(sq * (1.0f / 64.0f) + 1e-6f);
; #pragma unroll
;                     for (int bj = 0; bj < 2; ++bj) { const f32x4 a = t[bj][0] * rn * gv[bj][0], b = t[bj][1] * rn * gv[bj][1];
;                         u32x4 w; w.x = cvt_pk_bf16(a[0], a[1]); w.y = cvt_pk_bf16(a[2], a[3]); w.z = cvt_pk_bf16(b[0], b[1]); w.w = cvt_pk_bf16(b[2], b[3]);
;                         *(u32x4*)(dst + (size_t)row * 512 + head * 64 + 32 * bj + 8 * fq) = w; } }
.Lrm_orig_27:
	global_store_dwordx4 v[50:51], v[24:27], off offset:64
.Lrm_done_27:
	s_mov_b64 s[0:1], 0x28000
	v_lshl_add_u64 v[34:35], v[128:129], 0, s[0:1]
	v_fma_f32 v24, -v37, v38, 1.0
	v_fmac_f32_e32 v38, v24, v38
	v_div_scale_f32 v24, vcc, 1.0, v36, 1.0
	v_mul_f32_e32 v25, v24, v38
	v_fma_f32 v26, -v37, v25, v24
	v_fmac_f32_e32 v25, v26, v38
	v_fma_f32 v24, -v37, v25, v24
	v_div_fmas_f32 v24, v24, v38, v25
	v_div_fixup_f32 v32, v24, v36, 1.0
	v_pk_mul_f32 v[24:25], v[28:29], v[32:33] op_sel_hi:[1,0]
	v_pk_mul_f32 v[26:27], v[30:31], v[32:33] op_sel_hi:[1,0]
	v_pk_mul_f32 v[30:31], v[52:53], v[32:33] op_sel_hi:[1,0]
	v_pk_mul_f32 v[26:27], v[126:127], v[26:27]
	v_pk_mul_f32 v[24:25], v[124:125], v[24:25]
	v_pk_mul_f32 v[28:29], v[54:55], v[32:33] op_sel_hi:[1,0]
	v_pk_mul_f32 v[30:31], v[122:123], v[30:31]
	v_pk_mul_f32 v[28:29], v[120:121], v[28:29]
	v_cvt_pk_bf16_f32 v24, v24, v25
	v_cvt_pk_bf16_f32 v25, v26, v27
	s_mov_b32 s0, 0x28000
	v_cvt_pk_bf16_f32 v26, v28, v29
	v_cvt_pk_bf16_f32 v27, v30, v31
	v_mov_b32_e32 v30, v163
	v_pk_mul_f32 v[14:15], v[14:15], v[30:31] op_sel_hi:[1,0]
	v_pk_mul_f32 v[12:13], v[12:13], v[30:31] op_sel_hi:[1,0]
	v_pk_mul_f32 v[36:37], v[14:15], v[14:15]
	v_pk_mul_f32 v[38:39], v[12:13], v[12:13]
	v_pk_mul_f32 v[10:11], v[10:11], v[30:31] op_sel_hi:[1,0]
	v_pk_mov_b32 v[40:41], v[38:39], v[36:37] op_sel:[1,0]
	v_mov_b32_e32 v39, v37
	v_pk_add_f32 v[36:37], v[40:41], v[38:39]
	v_pk_mul_f32 v[8:9], v[8:9], v[30:31] op_sel_hi:[1,0]
	v_pk_add_f32 v[36:37], v[36:37], v[36:37] op_sel_hi:[0,1]
	v_pk_mul_f32 v[38:39], v[10:11], v[10:11]
	v_pk_mul_f32 v[40:41], v[8:9], v[8:9]
	v_pk_mul_f32 v[4:5], v[4:5], v[30:31] op_sel_hi:[1,0]
	v_pk_mov_b32 v[42:43], v[40:41], v[38:39] op_sel:[1,0]
	v_mov_b32_e32 v41, v39
	v_pk_mul_f32 v[6:7], v[6:7], v[30:31] op_sel_hi:[1,0]
	v_mul_f32_e32 v36, v4, v4
	v_pk_add_f32 v[38:39], v[42:43], v[40:41]
	v_pk_fma_f32 v[40:41], v[4:5], v[4:5], v[36:37] op_sel_hi:[1,1,0]
	v_mul_f32_e32 v36, v6, v6
	v_pk_add_f32 v[38:39], v[38:39], v[38:39] op_sel_hi:[0,1]
	v_pk_fma_f32 v[42:43], v[6:7], v[6:7], v[36:37] op_sel_hi:[1,1,0]
	v_pk_mul_f32 v[44:45], v[2:3], v[30:31] op_sel_hi:[1,0]
	v_pk_mul_f32 v[30:31], v[0:1], v[30:31] op_sel_hi:[1,0]
	v_mul_f32_e32 v36, v44, v44
	v_mul_f32_e32 v40, v30, v30
	v_mul_f32_e32 v42, v31, v31
	v_mul_f32_e32 v38, v45, v45
	v_pk_add_f32 v[0:1], v[40:41], v[42:43]
	v_pk_add_f32 v[2:3], v[36:37], v[38:39]
	v_add_co_u32_e32 v28, vcc, s0, v128
	v_pk_add_f32 v[0:1], v[0:1], v[2:3]
	s_nop 0
	v_addc_co_u32_e32 v29, vcc, 0, v129, vcc
	v_add_f32_e32 v33, v0, v1
	ds_bpermute_b32 v36, v140, v33
	v_pk_mul_f32 v[0:1], v[20:21], v[32:33] op_sel_hi:[1,0]
	v_pk_mul_f32 v[2:3], v[22:23], v[32:33] op_sel_hi:[1,0]
	v_pk_mul_f32 v[0:1], v[116:117], v[0:1]
	v_pk_mul_f32 v[2:3], v[118:119], v[2:3]
	s_waitcnt lgkmcnt(0)
	v_add_f32_e32 v20, v33, v36
	ds_bpermute_b32 v21, v141, v20
	s_mov_b64 vcc, s[100:101]
	s_cbranch_vccz .Lrm_orig_28
	v_accvgpr_write_b32 a0, v224
	v_accvgpr_write_b32 a1, v225
	v_accvgpr_write_b32 a2, v226
	v_accvgpr_write_b32 a3, v228
	v_accvgpr_write_b32 a4, v229
	v_subrev_u32_e32 v224, s98, v28
	v_lshrrev_b32_e32 v225, 10, v224
	v_and_b32_e32 v226, 0x3ff, v224
	v_lshrrev_b32_e32 v228, 7, v226
	v_mul_u32_u24_e32 v228, 0x204000, v228
	v_and_b32_e32 v226, 0x70, v226
	v_lshl_add_u32 v228, v226, 5, v228
	v_add_u32_e32 v229, 0x80, v225
	v_and_b32_e32 v226, 0xff, v225
	v_cmp_gt_u32_e32 vcc, 16, v226
	v_and_b32_e32 v224, 63, v226
	v_add_u32_e32 v226, 0x70, v226
	s_nop 1
	v_cndmask_b32_e32 v224, v224, v226, vcc
	v_cmp_lt_u32_e32 vcc, 0x3fff, v225
	s_nop 2
	v_cndmask_b32_e32 v229, v229, v224, vcc
	v_lshrrev_b32_e32 v224, 5, v229
	v_lshl_add_u32 v228, v224, 12, v228
	v_and_b32_e32 v224, 31, v229
	v_lshl_add_u32 v228, v224, 4, v228
	v_mov_b32_e32 v229, 0
	v_lshl_add_u64 v[224:225], s[98:99], 0, v[228:229]
	v_cmp_ne_u32_e64 vcc, s100, 0
	s_nop 2
	v_cndmask_b32_e32 v224, v28, v224, vcc
	v_cndmask_b32_e32 v225, v29, v225, vcc
	global_store_dwordx4 v[224:225], v[24:27], off
	s_nop 1
	v_accvgpr_read_b32 v224, a0
	v_accvgpr_read_b32 v225, a1
	v_accvgpr_read_b32 v226, a2
	v_accvgpr_read_b32 v228, a3
	v_accvgpr_read_b32 v229, a4
	s_branch .Lrm_done_28
.Lrm_orig_28:
	global_store_dwordx4 v[28:29], v[24:27], off
.Lrm_done_28:
	v_cvt_pk_bf16_f32 v0, v0, v1
	v_cvt_pk_bf16_f32 v1, v2, v3
	v_pk_mul_f32 v[16:17], v[16:17], v[32:33] op_sel_hi:[1,0]
	s_waitcnt lgkmcnt(0)
	v_add_f32_e32 v20, v20, v21
	v_fmamk_f32 v20, v20, 0x3c800000, v186
	v_mul_f32_e32 v21, 0x4f800000, v20
	v_cmp_gt_f32_e32 vcc, s50, v20
	v_pk_mul_f32 v[18:19], v[18:19], v[32:33] op_sel_hi:[1,0]
	v_pk_mul_f32 v[16:17], v[112:113], v[16:17]
	v_cndmask_b32_e32 v20, v20, v21, vcc
	v_sqrt_f32_e32 v21, v20
	v_pk_mul_f32 v[18:19], v[114:115], v[18:19]
	v_add_u32_e32 v2, -1, v21
	v_fma_f32 v3, -v2, v21, v20
	v_cmp_ge_f32_e64 s[4:5], 0, v3
	v_add_u32_e32 v3, 1, v21
	s_nop 0
	v_cndmask_b32_e64 v2, v21, v2, s[4:5]
	v_fma_f32 v21, -v3, v21, v20
	v_cmp_lt_f32_e64 s[4:5], 0, v21
	s_nop 1
	v_cndmask_b32_e64 v2, v2, v3, s[4:5]
	v_mul_f32_e32 v3, 0x37800000, v2
	v_cndmask_b32_e32 v2, v2, v3, vcc
	v_cmp_class_f32_e32 vcc, v20, v187
	s_nop 1
	v_cndmask_b32_e32 v20, v2, v20, vcc
	v_div_scale_f32 v21, s[0:1], v20, v20, 1.0
	v_rcp_f32_e32 v22, v21
	v_cvt_pk_bf16_f32 v2, v16, v17
	v_cvt_pk_bf16_f32 v3, v18, v19
	s_mov_b64 vcc, s[100:101]
	s_cbranch_vccz .Lrm_orig_29
	v_accvgpr_write_b32 a0, v224
	v_accvgpr_write_b32 a1, v225
	v_accvgpr_write_b32 a2, v226
	v_accvgpr_write_b32 a3, v228
	v_accvgpr_write_b32 a4, v229
	v_subrev_u32_e32 v224, s98, v34
	v_add_u32_e32 v224, 64, v224
	v_lshrrev_b32_e32 v225, 10, v224
	v_and_b32_e32 v226, 0x3ff, v224
	v_lshrrev_b32_e32 v228, 7, v226
	v_mul_u32_u24_e32 v228, 0x204000, v228
	v_and_b32_e32 v226, 0x70, v226
	v_lshl_add_u32 v228, v226, 5, v228
	v_add_u32_e32 v229, 0x80, v225
	v_and_b32_e32 v226, 0xff, v225
	v_cmp_gt_u32_e32 vcc, 16, v226
	v_and_b32_e32 v224, 63, v226
	v_add_u32_e32 v226, 0x70, v226
	s_nop 1
	v_cndmask_b32_e32 v224, v224, v226, vcc
	v_cmp_lt_u32_e32 vcc, 0x3fff, v225
	s_nop 2
	v_cndmask_b32_e32 v229, v229, v224, vcc
	v_lshrrev_b32_e32 v224, 5, v229
	v_lshl_add_u32 v228, v224, 12, v228
	v_and_b32_e32 v224, 31, v229
	v_lshl_add_u32 v228, v224, 4, v228
	v_mov_b32_e32 v229, 0
	v_lshl_add_u64 v[224:225], s[98:99], 0, v[228:229]
	v_lshl_add_u64 v[228:229], v[34:35], 0, 64
	v_cmp_ne_u32_e64 vcc, s100, 0
	s_nop 2
	v_cndmask_b32_e32 v224, v228, v224, vcc
	v_cndmask_b32_e32 v225, v229, v225, vcc
	global_store_dwordx4 v[224:225], v[0:3], off
	s_nop 1
	v_accvgpr_read_b32 v224, a0
	v_accvgpr_read_b32 v225, a1
	v_accvgpr_read_b32 v226, a2
	v_accvgpr_read_b32 v228, a3
	v_accvgpr_read_b32 v229, a4
	s_branch .Lrm_done_29
; __device__ __forceinline__ unsigned cvt_pk_bf16(float lo, float hi) { unsigned r; asm volatile("v_cvt_pk_bf16_f32 %0, %1, %2" : "=v"(r) : "v"(lo), "v"(hi)); return r; }
;     __device__ __forceinline__ void operator()(const f32x4 (&acc)[2][2][4][2], const Unit& u, int wr, int wc, int fr, int fq) const {
;     ...
;                 for (int m = 0; m < 4; ++m) { const int row = row0 + ai * HALF + m * 16; const float rs = rsv[ai][m]; float sq = 0.f; f32x4 t[2][2];
; #pragma unroll
;                     for (int bj = 0; bj < 2; ++bj)
; #pragma unroll
;                         for (int n = 0; n < 2; ++n) { t[bj][n] = acc[ai][bj][m][n] * rs; sq += (t[bj][n][0] * t[bj][n][0] + t[bj][n][1] * t[bj][n][1]) + (t[bj][n][2] * t[bj][n][2] + t[bj][n][3] * t[bj][n][3]); }
;                     sq += __shfl_xor(sq, 16); sq += __shfl_xor(sq, 32);
;                     const float rn = 1.0f / sqrtf(sq * (1.0f / 64.0f) + 1e-6f);
; #pragma unroll
;                     for (int bj = 0; bj < 2; ++bj) { const f32x4 a = t[bj][0] * rn * gv[bj][0], b = t[bj][1] * rn * gv[bj][1];
;                         u32x4 w; w.x = cvt_pk_bf16(a[0], a[1]); w.y = cvt_pk_bf16(a[2], a[3]); w.z = cvt_pk_bf16(b[0], b[1]); w.w = cvt_pk_bf16(b[2], b[3]);
;                         *(u32x4*)(dst + (size_t)row * 512 + head * 64 + 32 * bj + 8 * fq) = w; } }
.Lrm_orig_29:
	global_store_dwordx4 v[34:35], v[0:3], off offset:64
.Lrm_done_29:
	v_lshl_add_u64 v[18:19], v[128:129], 0, s[18:19]
	s_nop 0
	v_fma_f32 v0, -v21, v22, 1.0
	v_fmac_f32_e32 v22, v0, v22
	v_div_scale_f32 v0, vcc, 1.0, v20, 1.0
	v_mul_f32_e32 v1, v0, v22
	v_fma_f32 v2, -v21, v1, v0
	v_fmac_f32_e32 v1, v2, v22
	v_fma_f32 v0, -v21, v1, v0
	v_div_fmas_f32 v0, v0, v22, v1
	v_div_fixup_f32 v16, v0, v20, 1.0
	v_pk_mul_f32 v[0:1], v[12:13], v[16:17] op_sel_hi:[1,0]
	v_pk_mul_f32 v[2:3], v[14:15], v[16:17] op_sel_hi:[1,0]
	v_pk_mul_f32 v[8:9], v[8:9], v[16:17] op_sel_hi:[1,0]
	v_pk_mul_f32 v[2:3], v[126:127], v[2:3]
	v_pk_mul_f32 v[0:1], v[124:125], v[0:1]
	v_pk_mul_f32 v[8:9], v[120:121], v[8:9]
	v_pk_mul_f32 v[10:11], v[10:11], v[16:17] op_sel_hi:[1,0]
	v_cvt_pk_bf16_f32 v0, v0, v1
	v_cvt_pk_bf16_f32 v1, v2, v3
	v_cvt_pk_bf16_f32 v2, v8, v9
	v_add_co_u32_e32 v8, vcc, s51, v128
	v_pk_mul_f32 v[10:11], v[122:123], v[10:11]
	s_nop 0
	v_addc_co_u32_e32 v9, vcc, 0, v129, vcc
	v_cvt_pk_bf16_f32 v3, v10, v11
	s_mov_b64 vcc, s[100:101]
	s_cbranch_vccz .Lrm_orig_30
	v_accvgpr_write_b32 a0, v224
	v_accvgpr_write_b32 a1, v225
	v_accvgpr_write_b32 a2, v226
	v_accvgpr_write_b32 a3, v228
	v_accvgpr_write_b32 a4, v229
	v_subrev_u32_e32 v224, s98, v8
	v_lshrrev_b32_e32 v225, 10, v224
	v_and_b32_e32 v226, 0x3ff, v224
	v_lshrrev_b32_e32 v228, 7, v226
	v_mul_u32_u24_e32 v228, 0x204000, v228
	v_and_b32_e32 v226, 0x70, v226
	v_lshl_add_u32 v228, v226, 5, v228
	v_add_u32_e32 v229, 0x80, v225
	v_and_b32_e32 v226, 0xff, v225
	v_cmp_gt_u32_e32 vcc, 16, v226
	v_and_b32_e32 v224, 63, v226
	v_add_u32_e32 v226, 0x70, v226
	s_nop 1
	v_cndmask_b32_e32 v224, v224, v226, vcc
	v_cmp_lt_u32_e32 vcc, 0x3fff, v225
	s_nop 2
	v_cndmask_b32_e32 v229, v229, v224, vcc
	v_lshrrev_b32_e32 v224, 5, v229
	v_lshl_add_u32 v228, v224, 12, v228
	v_and_b32_e32 v224, 31, v229
	v_lshl_add_u32 v228, v224, 4, v228
	v_mov_b32_e32 v229, 0
	v_lshl_add_u64 v[224:225], s[98:99], 0, v[228:229]
	v_cmp_ne_u32_e64 vcc, s100, 0
	s_nop 2
	v_cndmask_b32_e32 v224, v8, v224, vcc
	v_cndmask_b32_e32 v225, v9, v225, vcc
	global_store_dwordx4 v[224:225], v[0:3], off
	s_nop 1
	v_accvgpr_read_b32 v224, a0
	v_accvgpr_read_b32 v225, a1
	v_accvgpr_read_b32 v226, a2
	v_accvgpr_read_b32 v228, a3
	v_accvgpr_read_b32 v229, a4
	s_branch .Lrm_done_30
.Lrm_orig_30:
	global_store_dwordx4 v[8:9], v[0:3], off
.Lrm_done_30:
	s_nop 1
	v_pk_mul_f32 v[0:1], v[4:5], v[16:17] op_sel_hi:[1,0]
	v_pk_mul_f32 v[2:3], v[6:7], v[16:17] op_sel_hi:[1,0]
	v_pk_mul_f32 v[0:1], v[116:117], v[0:1]
	v_pk_mul_f32 v[2:3], v[118:119], v[2:3]
	v_pk_mul_f32 v[4:5], v[30:31], v[16:17] op_sel_hi:[1,0]
	v_pk_mul_f32 v[6:7], v[44:45], v[16:17] op_sel_hi:[1,0]
	v_pk_mul_f32 v[4:5], v[112:113], v[4:5]
	v_pk_mul_f32 v[6:7], v[114:115], v[6:7]
	v_cvt_pk_bf16_f32 v0, v0, v1
	v_cvt_pk_bf16_f32 v1, v2, v3
	v_cvt_pk_bf16_f32 v2, v4, v5
	s_nop 0
	v_cvt_pk_bf16_f32 v3, v6, v7
	s_mov_b64 vcc, s[100:101]
	s_cbranch_vccz .Lrm_orig_31
	v_accvgpr_write_b32 a0, v224
	v_accvgpr_write_b32 a1, v225
	v_accvgpr_write_b32 a2, v226
	v_accvgpr_write_b32 a3, v228
	v_accvgpr_write_b32 a4, v229
	v_subrev_u32_e32 v224, s98, v18
	v_add_u32_e32 v224, 64, v224
	v_lshrrev_b32_e32 v225, 10, v224
	v_and_b32_e32 v226, 0x3ff, v224
	v_lshrrev_b32_e32 v228, 7, v226
	v_mul_u32_u24_e32 v228, 0x204000, v228
	v_and_b32_e32 v226, 0x70, v226
	v_lshl_add_u32 v228, v226, 5, v228
	v_add_u32_e32 v229, 0x80, v225
	v_and_b32_e32 v226, 0xff, v225
	v_cmp_gt_u32_e32 vcc, 16, v226
	v_and_b32_e32 v224, 63, v226
	v_add_u32_e32 v226, 0x70, v226
	s_nop 1
	v_cndmask_b32_e32 v224, v224, v226, vcc
	v_cmp_lt_u32_e32 vcc, 0x3fff, v225
	s_nop 2
	v_cndmask_b32_e32 v229, v229, v224, vcc
	v_lshrrev_b32_e32 v224, 5, v229
	v_lshl_add_u32 v228, v224, 12, v228
	v_and_b32_e32 v224, 31, v229
	v_lshl_add_u32 v228, v224, 4, v228
	v_mov_b32_e32 v229, 0
	v_lshl_add_u64 v[224:225], s[98:99], 0, v[228:229]
	v_lshl_add_u64 v[228:229], v[18:19], 0, 64
	v_cmp_ne_u32_e64 vcc, s100, 0
	s_nop 2
	v_cndmask_b32_e32 v224, v228, v224, vcc
	v_cndmask_b32_e32 v225, v229, v225, vcc
	global_store_dwordx4 v[224:225], v[0:3], off
	s_nop 1
	v_accvgpr_read_b32 v224, a0
	v_accvgpr_read_b32 v225, a1
	v_accvgpr_read_b32 v226, a2
	v_accvgpr_read_b32 v228, a3
	v_accvgpr_read_b32 v229, a4
	s_branch .Lrm_done_31
.Lrm_orig_31:
	global_store_dwordx4 v[18:19], v[0:3], off offset:64
.Lrm_done_31:
	s_andn2_b64 vcc, exec, s[6:7]
	s_mov_b64 s[4:5], -1
	s_cbranch_vccnz .LBB0_761
.LBB0_869:
	s_andn2_b64 vcc, exec, s[12:13]
	s_cbranch_vccnz .LBB0_760
	s_barrier
	s_branch .LBB0_760
